# attn loop: static 2-slot K ring (immediate LDS offsets, no per-read address VALU), merged lgkm waits, static prio split
# speedup vs baseline: 1.0155x; 1.0078x over previous
; __device__ __forceinline__ int v_st(int k, int c) { const int kk = (k & ~0xC) | ((k & 4) << 1) | ((k & 8) >> 1); return ((kk >> 3) * 4 + (c >> 5)) * 512 + ((kk & 7) * 32 + (c & 31)) * 2; }
; __device__ __forceinline__ int v_rd_base(int lane) { return ((lane & 3) << 3) | (((lane >> 2) & 3) << 6) | (((lane >> 4) & 1) << 5) | (((lane >> 5) & 1) << 8); }
; #define LBAR() do { asm volatile("s_waitcnt lgkmcnt(0)" ::: "memory"); __builtin_amdgcn_s_barrier(); asm volatile("" ::: "memory"); } while (0)
; __device__ __forceinline__ void attn_unit(const bf16_t* __restrict__ Qb, const bf16_t* __restrict__ Kn, const bf16_t* __restrict__ Vh, const bf16_t* __restrict__ Kr,
;                                           bf16_t* GO, int seq, char* lds, const int tid) {
;   const int wid = tid >> 6, lane = tid & 63, r32 = lane & 31, hi = lane >> 5;
;   char* V_lds = lds; char* K_lds = lds + 3 * SHM_V;
;   float* ws = (float*)(lds + 3 * SHM_V + 3 * SHM_K) + wid * 64; float* li_l = ws; float* al_l = ws + 32;
;   if (wid < 4) __builtin_amdgcn_s_setprio(2); else __builtin_amdgcn_s_setprio(0);
;   float m_reg = -1e30f, l_reg = 0; f32x16 o[4] = {}; bf16x8 qr[8];
;   char* qrl = lds + 3 * SHM_V + 3 * SHM_K + NW * 64 * 4 + wid * 4096 + r32 * 128;
;   const bf16_t* Qw = Qb + (long)(wid * QBLK + r32) * LDQ + hi * 8;
; #pragma unroll
;   for (int d0 = 0; d0 < 8; ++d0) qr[d0] = *reinterpret_cast<const bf16x8*>(Qw + d0 * 16);
; #pragma unroll
;   for (int d0 = 8; d0 < 12; ++d0) *reinterpret_cast<bf16x8*>(qrl + (((2 * (d0 - 8) + hi) ^ ((r32 >> 1) & 7)) << 4)) = *reinterpret_cast<const bf16x8*>(Qw + d0 * 16);
;   const int sr = tid >> 4, sc = (tid & 15) * 8, vst0 = v_st(sr, sc), vst1 = v_st(32 + sr, sc);
;   const int rr = tid >> 3, rc = (tid & 7) * 8;
;   const int vb0 = (int)(uintptr_t)V_lds + v_rd_base(lane);
;   const unsigned offkv = (unsigned)(sr * LDKV + sc) * 2u, offkr = (unsigned)(rr * LDKR + rc) * 2u;
;   struct { bf16x8 vs0, vs1, ks0, ks1, kr; } sr_[1];
;     ...
;   f32x16 pA0, pA1, pB0, pB1; float mnA, mnB, alA, alB; bf16x8 pa0, pa1, pa2, pa3; const int NT = seq / KVBLK;
;     ...
;   SLOAD(0, 0); SWRITE(0, 0); SLOAD(0, KVBLK); LBAR();
.Lattn_prio_done:
	s_add_u32 s55, s40, s34
	s_addc_u32 s56, s41, s35
	s_sub_i32 s18, s54, s20
	s_cmp_ge_u32 s54, s20
	s_cselect_b32 s18, s18, s54
	s_xor_b32 s18, s18, s51
	s_sub_i32 s18, s18, s51
	s_ashr_i32 s34, s53, 3
	s_ashr_i32 s35, s34, 31
	s_ashr_i32 s19, s18, 31
	s_and_b32 s51, s53, 7
	s_lshl_b64 s[40:41], s[34:35], s44
	s_lshl_b64 s[18:19], s[18:19], 8
	s_add_u32 s69, s40, s18
	s_addc_u32 s72, s41, s19
	s_add_u32 s53, s30, s28
	s_mul_i32 s18, s72, 0xc00
	s_mul_hi_u32 s19, s69, 0xc00
	s_addc_u32 s54, s31, s29
	s_add_i32 s19, s19, s18
	s_mul_i32 s18, s69, 0xc00
	s_add_u32 s18, s55, s18
	s_addc_u32 s19, s56, s19
	s_mul_i32 s34, s51, 0x180
	s_add_u32 s18, s18, s34
	s_addc_u32 s19, s19, 0
	v_and_b32_e32 v170, 31, v32
	v_lshlrev_b32_e32 v172, 5, v0
	v_bfe_u32 v171, v32, 5, 1
	v_or_b32_e32 v1, v172, v170
	v_mov_b64_e32 v[2:3], s[18:19]
	v_mad_i64_i32 v[2:3], s[18:19], v1, s49, v[2:3]
	v_lshlrev_b32_e32 v164, 4, v171
	v_mov_b32_e32 v165, v193
	v_lshl_add_u64 v[30:31], v[2:3], 0, v[164:165]
	global_load_dwordx4 v[2:5], v[30:31], off offset:256
	global_load_dwordx4 v[6:9], v[30:31], off offset:288
	s_lshl_b64 s[34:35], s[40:41], 12
	s_add_u32 s19, s53, s34
	s_addc_u32 s53, s54, s35
	s_lshl_b32 s18, s51, 9
	s_add_u32 s54, s19, s18
	s_addc_u32 s55, s53, 0
	v_lshlrev_b32_e32 v42, 3, v33
	s_add_u32 s40, s40, s42
	v_and_b32_e32 v18, 0x78, v42
	s_addc_u32 s41, s41, 0
	v_ashrrev_i32_e32 v1, 4, v33
	v_lshlrev_b32_e32 v43, 1, v18
	s_lshl_b64 s[56:57], s[40:41], 7
	s_add_i32 s19, 0, 0x1e000
	s_add_i32 s41, 0, 0x1e800
	v_lshl_or_b32 v68, v1, 12, v43
	v_mov_b32_e32 v69, v193
	v_and_b32_e32 v18, 56, v42
	s_cmp_lg_u32 0, -1
	v_lshl_add_u64 v[72:73], s[54:55], 0, v[68:69]
	v_ashrrev_i32_e32 v44, 3, v33
	s_cselect_b32 s40, 0, 0
	v_lshlrev_b32_e32 v192, 1, v18
	v_add_co_u32_e32 v34, vcc, s79, v72
	s_waitcnt lgkmcnt(0)
	s_add_u32 s38, s38, s56
	v_addc_co_u32_e32 v35, vcc, 0, v73, vcc
	v_lshl_or_b32 v38, v44, 7, v192
	v_mov_b32_e32 v39, v193
	s_addc_u32 s39, s39, s57
	global_load_dwordx4 v[10:13], v[30:31], off offset:320
	global_load_dwordx4 v[14:17], v[30:31], off offset:352
	global_load_dwordx4 v[18:21], v68, s[54:55] offset:256
	global_load_dwordx4 v[22:25], v[34:35], off offset:256
	global_load_dwordx4 v[26:29], v68, s[54:55]
	s_nop 0
	global_load_dwordx4 v[34:37], v[34:35], off
	v_lshl_add_u64 v[70:71], s[38:39], 0, v[38:39]
	s_mov_b32 s38, 0x13000000
	v_add_co_u32_e32 v38, vcc, s38, v70
	v_lshrrev_b32_e32 v45, 1, v33
	s_nop 0
	v_addc_co_u32_e32 v39, vcc, 0, v71, vcc
	global_load_dwordx4 v[38:41], v[38:39], off
	s_nop 0
	global_load_dwordx4 v[124:127], v[30:31], off
	global_load_dwordx4 v[120:123], v[30:31], off offset:32
	global_load_dwordx4 v[116:119], v[30:31], off offset:64
	global_load_dwordx4 v[112:115], v[30:31], off offset:96
	global_load_dwordx4 v[108:111], v[30:31], off offset:128
	global_load_dwordx4 v[104:107], v[30:31], off offset:160
	global_load_dwordx4 v[100:103], v[30:31], off offset:192
	global_load_dwordx4 v[96:99], v[30:31], off offset:224
	v_bfe_u32 v46, v33, 1, 3
	v_bitop3_b32 v47, v45, v171, 7 bitop3:0x6c
	v_lshl_add_u32 v165, v0, 12, s41
	v_bitop3_b32 v48, v171, v46, 2 bitop3:0x36
	v_lshlrev_b32_e32 v47, 4, v47
	v_lshl_add_u32 v0, v170, 7, v165
	v_lshlrev_b32_e32 v48, 4, v48
	v_add_u32_e32 v182, v0, v47
	v_add_u32_e32 v181, v0, v48
	s_mov_b32 s38, 0x13002000
	v_mul_u32_u24_e32 v47, 0x180, v170
	v_or_b32_e32 v80, 0x120, v164
	v_and_b32_e32 v174, 63, v32
	v_lshlrev_b32_e32 v79, 4, v32
	s_mov_b32 s53, s52
	s_mov_b32 s54, s52
	s_mov_b32 s55, s52
	s_waitcnt vmcnt(16)
	ds_write_b128 v182, v[2:5]
	s_waitcnt vmcnt(15)
	ds_write_b128 v181, v[6:9]
	v_bitop3_b32 v2, v171, v46, 4 bitop3:0x36
	v_lshlrev_b32_e32 v2, 4, v2
	v_add_u32_e32 v179, v0, v2
	v_bitop3_b32 v2, v171, v46, 6 bitop3:0x36
	v_lshlrev_b32_e32 v2, 4, v2
	v_add_u32_e32 v177, v0, v2
	v_and_b32_e32 v0, 0xfffff0, v1
	v_lshlrev_b32_e32 v2, 1, v1
	v_and_or_b32 v0, v2, 8, v0
	v_lshrrev_b32_e32 v2, 1, v1
	v_lshrrev_b32_e32 v0, 1, v0
	v_bfe_u32 v3, v42, 5, 2
	v_and_b32_e32 v4, 3, v1
	v_or_b32_e32 v0, v0, v3
	v_and_or_b32 v2, v2, 4, v4
	v_lshlrev_b32_e32 v0, 9, v0
	v_lshlrev_b32_e32 v2, 6, v2
	v_and_b32_e32 v4, 48, v43
	v_or3_b32 v183, v0, v2, v4
	v_add_u32_e32 v0, 32, v1
	v_and_b32_e32 v5, 0xfffff0, v0
	v_lshlrev_b32_e32 v0, 1, v0
	v_and_or_b32 v0, v0, 8, v5
	v_lshrrev_b32_e32 v0, 1, v0
	v_or_b32_e32 v0, v0, v3
	v_lshlrev_b32_e32 v0, 9, v0
	v_or3_b32 v184, v0, v2, v4
	v_mul_lo_u32 v0, v1, s8
	v_and_b32_e32 v1, 0x70, v45
	v_xad_u32 v185, v43, v1, v0
	v_add_u32_e32 v82, 0, v183
	v_add_u32_e32 v83, 0, v184
	v_add_u32_e32 v0, 0, v185
	s_waitcnt vmcnt(14)
	ds_write_b128 v179, v[10:13]
	s_waitcnt vmcnt(13)
	ds_write_b128 v177, v[14:17]
	s_waitcnt vmcnt(12)
	ds_write_b128 v82, v[18:21]
	s_waitcnt vmcnt(11)
	ds_write_b128 v83, v[22:25]
	s_waitcnt vmcnt(10)
	ds_write_b128 v0, v[26:29] offset:49152
	s_waitcnt vmcnt(9)
	ds_write_b128 v0, v[34:37] offset:61440
	v_mul_lo_u32 v0, v44, s8
	v_or_b32_e32 v1, 0x100, v192
	v_and_b32_e32 v2, 0x70, v33
	v_xad_u32 v186, v1, v2, v0
	v_add_u32_e32 v0, 0, v186
	s_waitcnt vmcnt(8)
	ds_write_b128 v0, v[38:41] offset:49152
	v_add_co_u32_e32 v0, vcc, s84, v72
	v_or_b32_e32 v34, 32, v164
	s_nop 0
	v_addc_co_u32_e32 v1, vcc, 0, v73, vcc
	v_add_co_u32_e32 v2, vcc, s85, v72
	v_lshlrev_b32_e32 v46, 4, v46
	s_nop 0
	v_addc_co_u32_e32 v3, vcc, 0, v73, vcc
	global_load_dwordx4 v[48:51], v[0:1], off offset:256
	global_load_dwordx4 v[52:55], v[0:1], off
	global_load_dwordx4 v[60:63], v[2:3], off offset:256
	global_load_dwordx4 v[56:59], v[2:3], off
	v_add_co_u32_e32 v0, vcc, s38, v70
	v_or_b32_e32 v42, 0x100, v164
	s_nop 0
	v_addc_co_u32_e32 v1, vcc, 0, v71, vcc
	global_load_dwordx4 v[64:67], v[0:1], off
	v_lshlrev_b32_e32 v0, 3, v32
	v_and_b32_e32 v78, 0x70, v0
	v_bitop3_b32 v199, v164, v47, v78 bitop3:0xde
	s_waitcnt lgkmcnt(0)
	s_barrier
; __device__ __forceinline__ void qkt(f32x16& p0, f32x16& p1, const char* Ks, const bf16x8* qr, const char* qrl, int r32, int hi) {
;   p0 = f32x16{}; p1 = f32x16{};
; #pragma unroll
;   for (int d0 = 0; d0 < 8; ++d0) { int cb = (d0 * 16 + hi * 8) * 2;
;     bf16x8 b0 = *reinterpret_cast<const bf16x8*>(Ks + KSWZ(r32, cb));
;     bf16x8 b1 = *reinterpret_cast<const bf16x8*>(Ks + KSWZ(32 + r32, cb));
;     p0 = __builtin_amdgcn_mfma_f32_32x32x16_bf16(b0, qr[d0], p0, 0, 0, 0);
;     p1 = __builtin_amdgcn_mfma_f32_32x32x16_bf16(b1, qr[d0], p1, 0, 0, 0); }
; #pragma unroll
;   for (int d0 = 8; d0 < 12; ++d0) { int cb = (d0 * 16 + hi * 8) * 2;
;     bf16x8 b0 = *reinterpret_cast<const bf16x8*>(Ks + KSWZ(r32, cb));
;     bf16x8 b1 = *reinterpret_cast<const bf16x8*>(Ks + KSWZ(32 + r32, cb));
;     bf16x8 qf = *reinterpret_cast<const bf16x8*>(qrl + (((2 * (d0 - 8) + hi) ^ ((r32 >> 1) & 7)) << 4));
;     p0 = __builtin_amdgcn_mfma_f32_32x32x16_bf16(b0, qf, p0, 0, 0, 0);
;     p1 = __builtin_amdgcn_mfma_f32_32x32x16_bf16(b1, qf, p1, 0, 0, 0); }
	v_add_u32_e32 v4, 0, v199
	ds_read_b128 v[0:3], v4 offset:49152
	ds_read_b128 v[16:19], v4 offset:61440
	s_waitcnt vmcnt(12) lgkmcnt(1)
	v_mfma_f32_32x32x16_bf16 v[0:15], v[0:3], v[124:127], 0
	v_bitop3_b32 v205, v34, v47, v78 bitop3:0xde
	v_add_u32_e32 v38, 0, v205
	ds_read_b128 v[34:37], v38 offset:49152
	ds_read_b128 v[38:41], v38 offset:61440
	v_xad_u32 v191, v42, v46, v47
	v_and_b32_e32 v33, 0x3fffffc0, v33
	v_xad_u32 v202, v42, v78, v47
	v_lshl_add_u32 v173, v33, 2, s19
	s_waitcnt lgkmcnt(2)
	v_mfma_f32_32x32x16_bf16 v[16:31], v[16:19], v[124:127], 0
	v_add_u32_e32 v33, 0, v202
	v_xad_u32 v198, v80, v46, v47
	v_xad_u32 v201, v80, v78, v47
	v_lshlrev_b32_e32 v32, 1, v32
	v_and_b32_e32 v32, 32, v32
	s_mov_b32 s19, 0x13004000
	s_mov_b32 s56, s52
	s_waitcnt vmcnt(11) lgkmcnt(1)
	v_mfma_f32_32x32x16_bf16 v[0:15], v[34:37], v[120:123], v[0:15]
	v_or_b32_e32 v34, 64, v164
	v_bitop3_b32 v206, v34, v47, v78 bitop3:0xde
	s_mov_b32 s57, s52
	s_mov_b32 s58, s52
	s_mov_b32 s59, s52
	s_mov_b32 s60, s52
	s_mov_b32 s61, s52
	s_waitcnt lgkmcnt(0)
	v_mfma_f32_32x32x16_bf16 v[16:31], v[38:41], v[120:123], v[16:31]
	v_add_u32_e32 v38, 0, v206
	ds_read_b128 v[34:37], v38 offset:49152
	ds_read_b128 v[38:41], v38 offset:61440
	s_mov_b32 s62, s52
	s_mov_b32 s63, s52
	s_mov_b32 s64, s52
	s_mov_b32 s65, s52
	s_mov_b32 s66, s52
	s_waitcnt vmcnt(10) lgkmcnt(1)
	v_mfma_f32_32x32x16_bf16 v[0:15], v[34:37], v[116:119], v[0:15]
	v_or_b32_e32 v34, 0x60, v164
	v_bitop3_b32 v208, v34, v47, v78 bitop3:0xde
	s_mov_b32 s67, s52
	s_mov_b32 s73, 2
	s_mov_b32 s76, 1
	v_cmp_gt_u32_e64 s[38:39], 32, v174
	v_lshl_add_u32 v175, v170, 2, v173
	s_waitcnt lgkmcnt(0)
	v_mfma_f32_32x32x16_bf16 v[16:31], v[38:41], v[116:119], v[16:31]
	v_add_u32_e32 v38, 0, v208
	ds_read_b128 v[34:37], v38 offset:49152
	ds_read_b128 v[38:41], v38 offset:61440
	v_mov_b32_e32 v176, 0
	s_waitcnt vmcnt(9) lgkmcnt(1)
	v_mfma_f32_32x32x16_bf16 v[0:15], v[34:37], v[112:115], v[0:15]
	v_or_b32_e32 v34, 0x80, v164
	v_xad_u32 v207, v34, v78, v47
	s_waitcnt lgkmcnt(0)
	v_mfma_f32_32x32x16_bf16 v[16:31], v[38:41], v[112:115], v[16:31]
	v_add_u32_e32 v38, 0, v207
	ds_read_b128 v[34:37], v38 offset:49152
	ds_read_b128 v[38:41], v38 offset:61440
	s_waitcnt vmcnt(8) lgkmcnt(1)
	v_mfma_f32_32x32x16_bf16 v[0:15], v[34:37], v[108:111], v[0:15]
	v_or_b32_e32 v34, 0xa0, v164
	v_xad_u32 v204, v34, v78, v47
	s_waitcnt lgkmcnt(0)
	v_mfma_f32_32x32x16_bf16 v[16:31], v[38:41], v[108:111], v[16:31]
	v_add_u32_e32 v38, 0, v204
	ds_read_b128 v[34:37], v38 offset:49152
	ds_read_b128 v[38:41], v38 offset:61440
	s_waitcnt vmcnt(7) lgkmcnt(1)
	v_mfma_f32_32x32x16_bf16 v[0:15], v[34:37], v[104:107], v[0:15]
	v_or_b32_e32 v34, 0xc0, v164
	v_xad_u32 v203, v34, v78, v47
	s_waitcnt lgkmcnt(0)
	v_mfma_f32_32x32x16_bf16 v[16:31], v[38:41], v[104:107], v[16:31]
	v_add_u32_e32 v38, 0, v203
	ds_read_b128 v[34:37], v38 offset:49152
	ds_read_b128 v[38:41], v38 offset:61440
	s_waitcnt vmcnt(6) lgkmcnt(1)
	v_mfma_f32_32x32x16_bf16 v[0:15], v[34:37], v[100:103], v[0:15]
	v_or_b32_e32 v34, 0xe0, v164
	v_xad_u32 v200, v34, v78, v47
	s_waitcnt lgkmcnt(0)
	v_mfma_f32_32x32x16_bf16 v[16:31], v[38:41], v[100:103], v[16:31]
	v_add_u32_e32 v38, 0, v200
	ds_read_b128 v[34:37], v38 offset:49152
	ds_read_b128 v[38:41], v38 offset:61440
	s_waitcnt vmcnt(5) lgkmcnt(1)
	v_mfma_f32_32x32x16_bf16 v[0:15], v[34:37], v[96:99], v[0:15]
	v_add_u32_e32 v34, 0, v191
	ds_read_b128 v[34:37], v34 offset:49152
	s_waitcnt lgkmcnt(1)
	v_mfma_f32_32x32x16_bf16 v[16:31], v[38:41], v[96:99], v[16:31]
	ds_read_b128 v[38:41], v182
	ds_read_b128 v[42:45], v33 offset:61440
	ds_read_b128 v[74:77], v181
	v_lshlrev_b32_e32 v33, 3, v174
	s_waitcnt lgkmcnt(2)
	v_mfma_f32_32x32x16_bf16 v[0:15], v[34:37], v[38:41], v[0:15]
	v_add_u32_e32 v34, 0, v198
	ds_read_b128 v[34:37], v34 offset:49152
	s_waitcnt lgkmcnt(2)
	v_mfma_f32_32x32x16_bf16 v[16:31], v[42:45], v[38:41], v[16:31]
	v_and_b32_e32 v38, 0xc0, v79
	v_and_or_b32 v42, v33, 24, v38
	v_add_u32_e32 v38, 0, v201
	ds_read_b128 v[38:41], v38 offset:61440
	v_and_b32_e32 v33, 0x100, v33
	v_or3_b32 v32, v42, v32, v33
	v_or_b32_e32 v42, 0x140, v164
	v_xad_u32 v187, v42, v46, v47
	v_add_u32_e32 v178, s40, v32
	v_add_u32_e32 v32, 0, v187
	s_waitcnt lgkmcnt(1)
	v_mfma_f32_32x32x16_bf16 v[0:15], v[34:37], v[74:77], v[0:15]
	ds_read_b128 v[32:35], v32 offset:49152
	v_or_b32_e32 v44, 0x160, v164
	v_xad_u32 v189, v42, v78, v47
	v_xad_u32 v188, v44, v46, v47
	v_xad_u32 v190, v44, v78, v47
	s_mov_b64 s[40:41], 0x13008000
	v_lshl_add_u64 v[166:167], v[70:71], 0, s[40:41]
	s_waitcnt lgkmcnt(1)
	v_mfma_f32_32x32x16_bf16 v[16:31], v[38:41], v[74:77], v[16:31]
	ds_read_b128 v[36:39], v179
	v_add_u32_e32 v40, 0, v189
	ds_read_b128 v[40:43], v40 offset:61440
	ds_read_b128 v[74:77], v177
	s_waitcnt lgkmcnt(2)
	v_mfma_f32_32x32x16_bf16 v[0:15], v[32:35], v[36:39], v[0:15]
	v_add_u32_e32 v32, 0, v188
	ds_read_b128 v[32:35], v32 offset:49152
	s_waitcnt lgkmcnt(2)
	v_mfma_f32_32x32x16_bf16 v[16:31], v[40:43], v[36:39], v[16:31]
	v_add_u32_e32 v36, 0, v190
	ds_read_b128 v[78:81], v36 offset:61440
	s_waitcnt lgkmcnt(1)
	v_mfma_f32_32x32x16_bf16 v[0:15], v[32:35], v[74:77], v[0:15]
	v_mov_b64_e32 v[32:33], s[52:53]
	v_mov_b64_e32 v[46:47], s[66:67]
	v_mov_b64_e32 v[34:35], s[54:55]
	v_mov_b64_e32 v[36:37], s[56:57]
	v_mov_b64_e32 v[38:39], s[58:59]
	v_mov_b64_e32 v[40:41], s[60:61]
	v_mov_b64_e32 v[42:43], s[62:63]
	s_waitcnt lgkmcnt(0)
; #define LBAR() do { asm volatile("s_waitcnt lgkmcnt(0)" ::: "memory"); __builtin_amdgcn_s_barrier(); asm volatile("" ::: "memory"); } while (0)
; __device__ __forceinline__ void partialSM(f32x16& p0, f32x16& p1, float& m_reg, float& mn, float& alpha) {
;   constexpr float C = SCALE * 1.4426950408889634f;
;   float pmax = p0[0];
; #pragma unroll
;   for (int r = 1; r < 16; ++r) pmax = fmaxf(pmax, p0[r]);
; #pragma unroll
;   for (int r = 0; r < 16; ++r) pmax = fmaxf(pmax, p1[r]);
;   { auto rr = __builtin_amdgcn_permlane32_swap(__float_as_uint(pmax), __float_as_uint(pmax), false, false);
;     pmax = fmaxf(__uint_as_float(rr[0]), __uint_as_float(rr[1])); }
;   if (__builtin_expect(__all(pmax - m_reg <= THR / SCALE), 1)) { mn = m_reg; alpha = 1.f; }
;   else { mn = fmaxf(m_reg, pmax); alpha = __builtin_amdgcn_exp2f((m_reg - mn) * C); m_reg = mn; }
;   float mnC = -mn * C;
; #pragma unroll
;   for (int r = 0; r < 16; ++r) p0[r] = fmaf(p0[r], C, mnC);
; #pragma unroll
;   for (int r = 0; r < 16; ++r) p1[r] = fmaf(p1[r], C, mnC);
; #pragma unroll
;   for (int r = 0; r < 16; ++r) p0[r] = __builtin_amdgcn_exp2f(p0[r]);
; }
; __device__ __forceinline__ void attn_unit(const bf16_t* __restrict__ Qb, const bf16_t* __restrict__ Kn, const bf16_t* __restrict__ Vh, const bf16_t* __restrict__ Kr,
;                                           bf16_t* GO, int seq, char* lds, const int tid) {
;     ...
;   SWRITE(1, 0); if (2 < NT) SLOAD(0, 2 * KVBLK); LBAR();
	v_mfma_f32_32x32x16_bf16 v[16:31], v[78:81], v[74:77], v[16:31]
	s_nop 2
	v_max_f32_e32 v74, v1, v1
	v_max_f32_e32 v75, v0, v0
	v_max_f32_e32 v74, v75, v74
	v_max3_f32 v74, v74, v2, v3
	v_max3_f32 v74, v74, v4, v5
	v_max3_f32 v74, v74, v6, v7
	v_max3_f32 v74, v74, v8, v9
	v_max3_f32 v74, v74, v10, v11
	v_max3_f32 v74, v74, v12, v13
	v_max3_f32 v74, v74, v14, v15
	v_max3_f32 v74, v74, v16, v17
	v_max3_f32 v74, v74, v18, v19
	v_max3_f32 v74, v74, v20, v21
	v_max3_f32 v74, v74, v22, v23
	v_max3_f32 v74, v74, v24, v25
	v_max3_f32 v74, v74, v26, v27
	v_max3_f32 v74, v74, v28, v29
	v_max3_f32 v76, v74, v30, v31
	v_mov_b32_e32 v74, v76
	s_nop 1
	v_permlane32_swap_b32_e32 v76, v74
	v_max_f32_e32 v77, v74, v74
	v_add_co_u32_e32 v74, vcc, s19, v70
	s_add_i32 s19, 0, 0x12000
	s_nop 0
	v_addc_co_u32_e32 v75, vcc, 0, v71, vcc
	global_load_dwordx4 v[128:131], v[74:75], off
	v_add_co_u32_e32 v74, vcc, s14, v72
	v_mov_b64_e32 v[44:45], s[64:65]
	s_nop 0
	v_addc_co_u32_e32 v75, vcc, 0, v73, vcc
	v_add_co_u32_e32 v72, vcc, s9, v72
	s_nop 1
	v_addc_co_u32_e32 v73, vcc, 0, v73, vcc
	global_load_dwordx4 v[132:135], v[74:75], off
	global_load_dwordx4 v[144:147], v[74:75], off offset:256
	global_load_dwordx4 v[136:139], v[72:73], off
	global_load_dwordx4 v[140:143], v[72:73], off offset:256
	v_max_f32_e32 v72, v76, v76
	v_max_f32_e32 v72, v72, v77
	v_add_f32_e32 v73, 0x7149f2ca, v72
	v_cmp_ge_f32_e32 vcc, s15, v73
	s_waitcnt vmcnt(9)
	ds_write_b128 v82, v[48:51] offset:16384
	s_waitcnt vmcnt(7)
	ds_write_b128 v83, v[60:63] offset:16384
	v_add_u32_e32 v48, s19, v185
	ds_write_b128 v48, v[52:55]
	s_waitcnt vmcnt(6)
	ds_write_b128 v48, v[56:59] offset:12288
	v_add_u32_e32 v48, s19, v186
	s_cmp_eq_u64 vcc, exec
	s_waitcnt vmcnt(5)
	ds_write_b128 v48, v[64:67]
	v_max_f32_e32 v49, 0xf149f2ca, v72
	s_cselect_b64 vcc, -1, 0
	v_mov_b32_e32 v48, 0xf149f2ca
	v_cndmask_b32_e32 v210, v49, v48, vcc
	v_mul_f32_e32 v48, 0xbdd53b94, v210
	v_fmamk_f32 v0, v0, 0x3dd53b94, v48
	v_exp_f32_e32 v225, v0
	v_fmamk_f32 v0, v1, 0x3dd53b94, v48
	v_exp_f32_e32 v228, v0
	v_fmamk_f32 v0, v2, 0x3dd53b94, v48
	v_exp_f32_e32 v226, v0
	v_fmamk_f32 v0, v3, 0x3dd53b94, v48
	v_exp_f32_e32 v229, v0
	v_fmamk_f32 v0, v4, 0x3dd53b94, v48
	v_exp_f32_e32 v227, v0
	v_fmamk_f32 v0, v5, 0x3dd53b94, v48
	v_exp_f32_e32 v230, v0
	v_fmamk_f32 v0, v6, 0x3dd53b94, v48
	v_exp_f32_e32 v223, v0
	v_fmamk_f32 v0, v7, 0x3dd53b94, v48
	v_exp_f32_e32 v224, v0
	v_fmamk_f32 v0, v8, 0x3dd53b94, v48
	v_exp_f32_e32 v219, v0
	v_fmamk_f32 v0, v9, 0x3dd53b94, v48
	v_exp_f32_e32 v221, v0
	v_fmamk_f32 v0, v10, 0x3dd53b94, v48
	s_add_u32 s19, s28, s34
	v_pk_fma_f32 v[156:157], v[22:23], s[16:17], v[48:49] op_sel_hi:[1,0,0]
	v_sub_f32_e32 v22, 0xf149f2ca, v49
	v_exp_f32_e32 v220, v0
	v_fmamk_f32 v0, v11, 0x3dd53b94, v48
	s_addc_u32 s28, s29, s35
	v_mul_f32_e32 v22, 0x3dd53b94, v22
	v_exp_f32_e32 v222, v0
	v_fmamk_f32 v0, v12, 0x3dd53b94, v48
	s_add_u32 s18, s19, s18
	v_exp_f32_e32 v22, v22
	v_exp_f32_e32 v215, v0
	v_fmamk_f32 v0, v13, 0x3dd53b94, v48
	s_addc_u32 s19, s28, 0
	v_pk_fma_f32 v[148:149], v[30:31], s[16:17], v[48:49] op_sel_hi:[1,0,0]
	v_pk_fma_f32 v[150:151], v[28:29], s[16:17], v[48:49] op_sel_hi:[1,0,0]
	v_pk_fma_f32 v[152:153], v[26:27], s[16:17], v[48:49] op_sel_hi:[1,0,0]
	v_pk_fma_f32 v[154:155], v[24:25], s[16:17], v[48:49] op_sel_hi:[1,0,0]
	v_pk_fma_f32 v[158:159], v[20:21], s[16:17], v[48:49] op_sel_hi:[1,0,0]
	v_pk_fma_f32 v[160:161], v[18:19], s[16:17], v[48:49] op_sel_hi:[1,0,0]
	v_pk_fma_f32 v[162:163], v[16:17], s[16:17], v[48:49] op_sel_hi:[1,0,0]
	v_exp_f32_e32 v217, v0
	v_fmamk_f32 v0, v14, 0x3dd53b94, v48
	v_fmac_f32_e32 v48, 0x3dd53b94, v15
	s_add_u32 s18, s30, s18
	v_exp_f32_e32 v216, v0
	v_exp_f32_e32 v218, v48
	s_addc_u32 s19, s31, s19
	s_waitcnt lgkmcnt(0)
	s_barrier
	v_lshl_add_u64 v[0:1], s[18:19], 0, v[68:69]
	s_mov_b64 s[18:19], 0x120100
	v_cndmask_b32_e64 v209, v22, 1.0, vcc
	v_lshl_add_u64 v[168:169], v[0:1], 0, s[18:19]
	v_mov_b64_e32 v[62:63], v[46:47]
	v_mov_b64_e32 v[16:17], v[32:33]
	v_mov_b64_e32 v[0:1], v[32:33]
	v_mov_b64_e32 v[60:61], v[44:45]
	v_mov_b64_e32 v[58:59], v[42:43]
	v_mov_b64_e32 v[56:57], v[40:41]
	v_mov_b64_e32 v[54:55], v[38:39]
	v_mov_b64_e32 v[52:53], v[36:37]
	v_mov_b64_e32 v[50:51], v[34:35]
	v_mov_b64_e32 v[48:49], v[32:33]
	v_mov_b64_e32 v[18:19], v[34:35]
	v_mov_b64_e32 v[20:21], v[36:37]
	v_mov_b64_e32 v[22:23], v[38:39]
	v_mov_b64_e32 v[24:25], v[40:41]
	v_mov_b64_e32 v[26:27], v[42:43]
	v_mov_b64_e32 v[28:29], v[44:45]
	v_mov_b64_e32 v[30:31], v[46:47]
	v_mov_b64_e32 v[2:3], v[34:35]
	v_mov_b64_e32 v[4:5], v[36:37]
	v_mov_b64_e32 v[6:7], v[38:39]
	v_mov_b64_e32 v[8:9], v[40:41]
	v_mov_b64_e32 v[10:11], v[42:43]
	v_mov_b64_e32 v[12:13], v[44:45]
	v_mov_b64_e32 v[14:15], v[46:47]
	v_add_u32_e32 v199, 0x9000, v199
	v_add_u32_e32 v205, 0x9000, v205
	v_add_u32_e32 v206, 0x9000, v206
	v_add_u32_e32 v208, 0x9000, v208
	v_add_u32_e32 v207, 0x9000, v207
	v_add_u32_e32 v204, 0x9000, v204
	v_add_u32_e32 v203, 0x9000, v203
	v_add_u32_e32 v200, 0x9000, v200
	v_add_u32_e32 v191, 0x9000, v191
	v_add_u32_e32 v198, 0x9000, v198
	v_add_u32_e32 v187, 0x9000, v187
	v_add_u32_e32 v188, 0x9000, v188
	v_add_u32_e32 v202, 0x9000, v202
	v_add_u32_e32 v201, 0x9000, v201
	v_add_u32_e32 v189, 0x9000, v189
	v_add_u32_e32 v190, 0x9000, v190
	v_add_u32_e32 v185, 0x9000, v185
	v_add_u32_e32 v186, 0x9000, v186
; __device__ __forceinline__ void finishSM(f32x16& p0, f32x16& p1, float alpha, float& l_reg, bf16x8& pa0, bf16x8& pa1, bf16x8& pa2, bf16x8& pa3) {
; #pragma unroll
;   for (int r = 0; r < 16; ++r) p1[r] = __builtin_amdgcn_exp2f(p1[r]);
;   float ps = 0;
; #pragma unroll
;   for (int r = 0; r < 16; ++r) ps += p0[r];
; #pragma unroll
;   for (int r = 0; r < 16; ++r) ps += p1[r];
;   { auto rr = __builtin_amdgcn_permlane32_swap(__float_as_uint(ps), __float_as_uint(ps), false, false);
;     ps = __uint_as_float(rr[0]) + __uint_as_float(rr[1]); }
;   l_reg = l_reg * alpha + ps;
; __device__ __forceinline__ void qkt(f32x16& p0, f32x16& p1, const char* Ks, const bf16x8* qr, const char* qrl, int r32, int hi) {
;   p0 = f32x16{}; p1 = f32x16{};
; #pragma unroll
;   for (int d0 = 0; d0 < 8; ++d0) { int cb = (d0 * 16 + hi * 8) * 2;
;     bf16x8 b0 = *reinterpret_cast<const bf16x8*>(Ks + KSWZ(r32, cb));
;     bf16x8 b1 = *reinterpret_cast<const bf16x8*>(Ks + KSWZ(32 + r32, cb));
;     p0 = __builtin_amdgcn_mfma_f32_32x32x16_bf16(b0, qr[d0], p0, 0, 0, 0);
;     p1 = __builtin_amdgcn_mfma_f32_32x32x16_bf16(b1, qr[d0], p1, 0, 0, 0); }
; #pragma unroll
;   for (int d0 = 8; d0 < 12; ++d0) { int cb = (d0 * 16 + hi * 8) * 2;
;     bf16x8 b0 = *reinterpret_cast<const bf16x8*>(Ks + KSWZ(r32, cb));
;     bf16x8 b1 = *reinterpret_cast<const bf16x8*>(Ks + KSWZ(32 + r32, cb));
;     bf16x8 qf = *reinterpret_cast<const bf16x8*>(qrl + (((2 * (d0 - 8) + hi) ^ ((r32 >> 1) & 7)) << 4));
;     p0 = __builtin_amdgcn_mfma_f32_32x32x16_bf16(b0, qf, p0, 0, 0, 0);
;     p1 = __builtin_amdgcn_mfma_f32_32x32x16_bf16(b1, qf, p1, 0, 0, 0); }
.LBB0_1151:
	s_sub_i32 s30, s76, 1
	s_cmp_eq_u32 s76, 0
	s_cselect_b32 s30, 2, s30
	s_add_i32 s18, s76, 1
	s_cmp_lg_u32 s76, 2
	s_cselect_b32 s18, s18, 0
	ds_read_b128 v[64:67], v199 offset:36864
	ds_read_b128 v[68:71], v199 offset:49152
	ds_read_b128 v[232:235], v205 offset:36864
	ds_read_b128 v[236:239], v205 offset:49152
	ds_read_b128 v[240:243], v206 offset:36864
	ds_read_b128 v[248:251], v206 offset:49152
	v_exp_f32_e32 v162, v162
	v_add_f32_e32 v211, v225, v228
	v_exp_f32_e32 v163, v163
	v_add_f32_e32 v211, v226, v211
	v_exp_f32_e32 v160, v160
	s_waitcnt lgkmcnt(4)
	v_mfma_f32_32x32x16_bf16 v[80:95], v[64:67], v[124:127], 0
	v_add_f32_e32 v211, v229, v211
	v_exp_f32_e32 v161, v161
	v_add_f32_e32 v211, v227, v211
	v_mfma_f32_32x32x16_bf16 v[64:79], v[68:71], v[124:127], 0
	v_exp_f32_e32 v158, v158
	v_add_f32_e32 v211, v230, v211
	s_waitcnt lgkmcnt(2)
	v_mfma_f32_32x32x16_bf16 v[80:95], v[232:235], v[120:123], v[80:95]
	ds_read_b128 v[232:235], v208 offset:36864
	v_exp_f32_e32 v159, v159
	v_add_f32_e32 v211, v223, v211
	v_mfma_f32_32x32x16_bf16 v[64:79], v[236:239], v[120:123], v[64:79]
	ds_read_b128 v[236:239], v208 offset:49152
	v_exp_f32_e32 v156, v156
	v_add_f32_e32 v211, v224, v211
	s_waitcnt lgkmcnt(2)
	v_mfma_f32_32x32x16_bf16 v[80:95], v[240:243], v[116:119], v[80:95]
	ds_read_b128 v[240:243], v207 offset:36864
	v_exp_f32_e32 v157, v157
	v_add_f32_e32 v211, v219, v211
	v_mfma_f32_32x32x16_bf16 v[64:79], v[248:251], v[116:119], v[64:79]
	ds_read_b128 v[248:251], v207 offset:49152
	v_exp_f32_e32 v154, v154
	v_add_f32_e32 v211, v221, v211
	s_waitcnt lgkmcnt(2)
	v_mfma_f32_32x32x16_bf16 v[80:95], v[232:235], v[112:115], v[80:95]
	ds_read_b128 v[232:235], v204 offset:36864
	v_exp_f32_e32 v155, v155
	v_add_f32_e32 v211, v220, v211
	v_mfma_f32_32x32x16_bf16 v[64:79], v[236:239], v[112:115], v[64:79]
	ds_read_b128 v[236:239], v204 offset:49152
	v_exp_f32_e32 v152, v152
	v_add_f32_e32 v211, v222, v211
	s_waitcnt lgkmcnt(2)
	v_mfma_f32_32x32x16_bf16 v[80:95], v[240:243], v[108:111], v[80:95]
	ds_read_b128 v[240:243], v203 offset:36864
	v_exp_f32_e32 v153, v153
	v_add_f32_e32 v211, v215, v211
	v_mfma_f32_32x32x16_bf16 v[64:79], v[248:251], v[108:111], v[64:79]
	ds_read_b128 v[248:251], v203 offset:49152
	v_exp_f32_e32 v150, v150
	v_add_f32_e32 v211, v217, v211
	s_waitcnt lgkmcnt(2)
	v_mfma_f32_32x32x16_bf16 v[80:95], v[232:235], v[104:107], v[80:95]
	ds_read_b128 v[232:235], v200 offset:36864
	v_exp_f32_e32 v151, v151
	v_add_f32_e32 v211, v216, v211
	v_mfma_f32_32x32x16_bf16 v[64:79], v[236:239], v[104:107], v[64:79]
	ds_read_b128 v[236:239], v200 offset:49152
	v_exp_f32_e32 v148, v148
	v_add_f32_e32 v211, v218, v211
	s_waitcnt lgkmcnt(2)
	v_mfma_f32_32x32x16_bf16 v[80:95], v[240:243], v[100:103], v[80:95]
	ds_read_b128 v[240:243], v191 offset:36864
	v_exp_f32_e32 v149, v149
	v_add_f32_e32 v212, v162, v163
	v_add_f32_e32 v212, v160, v212
	v_mfma_f32_32x32x16_bf16 v[64:79], v[248:251], v[100:103], v[64:79]
	ds_read_b128 v[248:251], v202 offset:49152
	v_add_f32_e32 v212, v161, v212
	v_add_f32_e32 v212, v158, v212
	v_add_f32_e32 v212, v159, v212
	v_add_f32_e32 v212, v156, v212
	s_waitcnt lgkmcnt(2)
	v_mfma_f32_32x32x16_bf16 v[80:95], v[232:235], v[96:99], v[80:95]
	ds_read_b128 v[232:235], v182
	v_add_f32_e32 v212, v157, v212
	v_add_f32_e32 v212, v154, v212
	v_add_f32_e32 v212, v155, v212
	v_add_f32_e32 v212, v152, v212
	v_mfma_f32_32x32x16_bf16 v[64:79], v[236:239], v[96:99], v[64:79]
	ds_read_b128 v[236:239], v198 offset:36864
	v_add_f32_e32 v212, v153, v212
	v_add_f32_e32 v212, v150, v212
	v_add_f32_e32 v212, v151, v212
	v_add_f32_e32 v212, v148, v212
	s_waitcnt lgkmcnt(1)
	v_mfma_f32_32x32x16_bf16 v[80:95], v[240:243], v[232:235], v[80:95]
	ds_read_b128 v[240:243], v201 offset:49152
	v_add_f32_e32 v212, v149, v212
	v_add_f32_e32 v211, v211, v212
	v_mov_b32_e32 v212, v211
	v_cvt_pk_bf16_f32 v158, v158, v159
	v_mfma_f32_32x32x16_bf16 v[64:79], v[248:251], v[232:235], v[64:79]
	ds_read_b128 v[248:251], v181
	ds_read_b128 v[232:235], v187 offset:36864
	v_cvt_pk_bf16_f32 v159, v156, v157
	v_permlane32_swap_b32_e32 v211, v212
	v_cvt_pk_bf16_f32 v156, v162, v163
	v_cvt_pk_bf16_f32 v157, v160, v161
	s_waitcnt lgkmcnt(1)
	v_mfma_f32_32x32x16_bf16 v[80:95], v[236:239], v[248:251], v[80:95]
	ds_read_b128 v[236:239], v189 offset:49152
	v_cvt_pk_bf16_f32 v160, v154, v155
	v_cvt_pk_bf16_f32 v161, v152, v153
	v_cvt_pk_bf16_f32 v162, v150, v151
	v_cvt_pk_bf16_f32 v163, v148, v149
	v_mfma_f32_32x32x16_bf16 v[64:79], v[240:243], v[248:251], v[64:79]
	ds_read_b128 v[240:243], v179
	ds_read_b128 v[248:251], v188 offset:36864
	v_add_f32_e32 v211, v211, v212
	v_cvt_pk_bf16_f32 v148, v225, v228
	v_cvt_pk_bf16_f32 v149, v226, v229
	v_cvt_pk_bf16_f32 v150, v227, v230
	s_waitcnt lgkmcnt(1)
	v_mfma_f32_32x32x16_bf16 v[80:95], v[232:235], v[240:243], v[80:95]
	ds_read_b128 v[232:235], v190 offset:49152
	v_cvt_pk_bf16_f32 v151, v223, v224
	v_cvt_pk_bf16_f32 v152, v219, v221
	v_cvt_pk_bf16_f32 v153, v220, v222
	v_cvt_pk_bf16_f32 v154, v215, v217
	v_mfma_f32_32x32x16_bf16 v[64:79], v[236:239], v[240:243], v[64:79]
	ds_read_b128 v[236:239], v177
	v_cvt_pk_bf16_f32 v155, v216, v218
	v_fma_f32 v176, v209, v176, v211
	s_nop 1
	v_permlane32_swap_b32_e32 v156, v158
	s_waitcnt lgkmcnt(0)
; #define SBAR() __builtin_amdgcn_sched_barrier(0)
; template <int D0> __device__ __forceinline__ void pv_one(f32x16& od, int vb, bf16x8 pa0, bf16x8 pa1, bf16x8 pa2, bf16x8 pa3) {
;   const s16x4 l0 = tr_read<v_rd_off(D0, 0, 0)>(vb), h0 = tr_read<v_rd_off(D0, 0, 1)>(vb), l1 = tr_read<v_rd_off(D0, 1, 0)>(vb), h1 = tr_read<v_rd_off(D0, 1, 1)>(vb);
;   const s16x4 l2 = tr_read<v_rd_off(D0, 2, 0)>(vb), h2 = tr_read<v_rd_off(D0, 2, 1)>(vb), l3 = tr_read<v_rd_off(D0, 3, 0)>(vb), h3 = tr_read<v_rd_off(D0, 3, 1)>(vb);
;   asm volatile("s_waitcnt lgkmcnt(0)" ::: "memory"); SBAR();
;     ...
;   od = __builtin_amdgcn_mfma_f32_32x32x16_bf16(pa0, PK(l0, h0), od, 0, 0, 0);
;   od = __builtin_amdgcn_mfma_f32_32x32x16_bf16(pa1, PK(l1, h1), od, 0, 0, 0);
;   od = __builtin_amdgcn_mfma_f32_32x32x16_bf16(pa2, PK(l2, h2), od, 0, 0, 0);
;   od = __builtin_amdgcn_mfma_f32_32x32x16_bf16(pa3, PK(l3, h3), od, 0, 0, 0);
;     ...
; }
; __device__ __forceinline__ void pv_d0(f32x16* o, int vb, bf16x8 pa0, bf16x8 pa1, bf16x8 pa2, bf16x8 pa3) {
;   pv_one<0>(o[0], vb, pa0, pa1, pa2, pa3); pv_one<1>(o[1], vb, pa0, pa1, pa2, pa3); pv_one<2>(o[2], vb, pa0, pa1, pa2, pa3); pv_one<3>(o[3], vb, pa0, pa1, pa2, pa3);
	v_mfma_f32_32x32x16_bf16 v[80:95], v[248:251], v[236:239], v[80:95]
	v_permlane32_swap_b32_e32 v157, v159
	v_permlane32_swap_b32_e32 v160, v162
	v_permlane32_swap_b32_e32 v161, v163
	v_permlane32_swap_b32_e32 v148, v150
	v_mfma_f32_32x32x16_bf16 v[64:79], v[232:235], v[236:239], v[64:79]
	v_permlane32_swap_b32_e32 v149, v151
	v_permlane32_swap_b32_e32 v152, v154
	v_permlane32_swap_b32_e32 v153, v155
	s_lshl_b32 s31, s30, 14
	v_add_u32_e32 v180, s31, v178
	ds_read_b64_tr_b16 v[240:241], v180 offset:0
	ds_read_b64_tr_b16 v[242:243], v180 offset:2048
	ds_read_b64_tr_b16 v[248:249], v180 offset:512
	ds_read_b64_tr_b16 v[250:251], v180 offset:2560
	ds_read_b64_tr_b16 v[232:233], v180 offset:1024
	ds_read_b64_tr_b16 v[234:235], v180 offset:3072
	ds_read_b64_tr_b16 v[236:237], v180 offset:1536
	ds_read_b64_tr_b16 v[238:239], v180 offset:3584
	s_lshl_b32 s19, s18, 14
	v_add_u32_e32 v231, s19, v183
	s_waitcnt vmcnt(0)
	ds_write_b128 v231, v[140:143]
	v_add_u32_e32 v140, s19, v184
	ds_write_b128 v140, v[144:147]
	ds_write_b128 v185, v[136:139] offset:12288
	ds_write_b128 v185, v[132:135] offset:24576
	s_mov_b32 s18, 0xfffa0000
	ds_write_b128 v186, v[128:131] offset:12288
	v_add_co_u32_e32 v128, vcc, s18, v168
	s_mov_b32 s18, 0xfffc0000
	s_nop 0
	v_addc_co_u32_e32 v129, vcc, -1, v169, vcc
	v_add_co_u32_e32 v130, vcc, s18, v168
	s_movk_i32 s18, 0xe000
	s_nop 0
	v_addc_co_u32_e32 v131, vcc, -1, v169, vcc
	global_load_dwordx4 v[140:143], v[128:129], off
	global_load_dwordx4 v[136:139], v[128:129], off offset:-256
	global_load_dwordx4 v[144:147], v[130:131], off
	global_load_dwordx4 v[132:135], v[130:131], off offset:-256
	v_add_co_u32_e32 v128, vcc, s18, v166
	s_nop 1
	v_addc_co_u32_e32 v129, vcc, -1, v167, vcc
	global_load_dwordx4 v[128:131], v[128:129], off
	v_max3_f32 v194, v80, v81, v82
	v_max3_f32 v195, v64, v65, v66
	v_max3_f32 v194, v194, v83, v84
	v_max3_f32 v195, v195, v67, v68
	v_max3_f32 v194, v194, v85, v86
	v_max3_f32 v195, v195, v69, v70
	s_waitcnt lgkmcnt(9)
	v_mfma_f32_32x32x16_bf16 v[32:47], v[148:151], v[240:243], v[32:47]
	ds_read_b64_tr_b16 v[240:241], v180 offset:4096
	ds_read_b64_tr_b16 v[242:243], v180 offset:6144
	v_max3_f32 v194, v194, v87, v88
	v_max3_f32 v195, v195, v71, v72
	v_max3_f32 v194, v194, v89, v90
	v_max3_f32 v195, v195, v73, v74
	v_max3_f32 v194, v194, v91, v92
	v_max3_f32 v195, v195, v75, v76
	v_mfma_f32_32x32x16_bf16 v[48:63], v[148:151], v[248:251], v[48:63]
	ds_read_b64_tr_b16 v[248:249], v180 offset:4608
	ds_read_b64_tr_b16 v[250:251], v180 offset:6656
	v_max3_f32 v194, v194, v93, v94
	v_max3_f32 v195, v195, v77, v78
	v_max3_f32 v194, v194, v95, v195
	v_max_f32_e32 v194, v194, v79
	v_mov_b32_e32 v195, v194
	s_nop 1
	s_waitcnt lgkmcnt(9)
	v_mfma_f32_32x32x16_bf16 v[16:31], v[148:151], v[232:235], v[16:31]
	ds_read_b64_tr_b16 v[232:233], v180 offset:5120
	ds_read_b64_tr_b16 v[234:235], v180 offset:7168
	v_permlane32_swap_b32_e32 v194, v195
	v_max_f32_e32 v194, v194, v195
	v_sub_f32_e32 v195, v194, v210
	v_cmp_ge_f32_e32 vcc, s15, v195
	v_max_f32_e32 v194, v210, v194
	v_sub_f32_e32 v195, v210, v194
	v_mfma_f32_32x32x16_bf16 v[0:15], v[148:151], v[236:239], v[0:15]
	ds_read_b64_tr_b16 v[236:237], v180 offset:5632
	ds_read_b64_tr_b16 v[238:239], v180 offset:7680
	v_mul_f32_e32 v195, 0x3dd53b94, v195
	v_exp_f32_e32 v195, v195
	s_cmp_eq_u64 vcc, exec
	s_cselect_b64 s[40:41], -1, 0
	v_cndmask_b32_e64 v214, v195, 1.0, s[40:41]
	s_waitcnt lgkmcnt(4)
	v_mfma_f32_32x32x16_bf16 v[32:47], v[152:155], v[240:243], v[32:47]
	ds_read_b64_tr_b16 v[240:241], v180 offset:8192
	ds_read_b64_tr_b16 v[242:243], v180 offset:10240
	v_cndmask_b32_e64 v210, v194, v210, s[40:41]
	v_mul_f32_e32 v194, 0xbdd53b94, v210
	v_fmamk_f32 v80, v80, 0x3dd53b94, v194
	v_fmamk_f32 v81, v81, 0x3dd53b94, v194
	v_fmamk_f32 v82, v82, 0x3dd53b94, v194
	v_mfma_f32_32x32x16_bf16 v[48:63], v[152:155], v[248:251], v[48:63]
	ds_read_b64_tr_b16 v[248:249], v180 offset:8704
	ds_read_b64_tr_b16 v[250:251], v180 offset:10752
	v_exp_f32_e32 v225, v80
	v_fmamk_f32 v83, v83, 0x3dd53b94, v194
	v_exp_f32_e32 v228, v81
	v_fmamk_f32 v150, v76, 0x3dd53b94, v194
	s_waitcnt lgkmcnt(4)
	v_mfma_f32_32x32x16_bf16 v[16:31], v[152:155], v[232:235], v[16:31]
	ds_read_b64_tr_b16 v[232:233], v180 offset:9216
	ds_read_b64_tr_b16 v[234:235], v180 offset:11264
	v_fmamk_f32 v151, v77, 0x3dd53b94, v194
	v_fmamk_f32 v148, v78, 0x3dd53b94, v194
	v_fmamk_f32 v149, v79, 0x3dd53b94, v194
	v_fmamk_f32 v84, v84, 0x3dd53b94, v194
	v_exp_f32_e32 v226, v82
	v_mfma_f32_32x32x16_bf16 v[0:15], v[152:155], v[236:239], v[0:15]
	ds_read_b64_tr_b16 v[236:237], v180 offset:9728
	ds_read_b64_tr_b16 v[238:239], v180 offset:11776
	v_fmamk_f32 v85, v85, 0x3dd53b94, v194
	v_exp_f32_e32 v229, v83
	v_fmamk_f32 v86, v86, 0x3dd53b94, v194
	v_exp_f32_e32 v227, v84
	s_waitcnt lgkmcnt(4)
	v_mfma_f32_32x32x16_bf16 v[32:47], v[156:159], v[240:243], v[32:47]
	ds_read_b64_tr_b16 v[240:241], v180 offset:12288
	ds_read_b64_tr_b16 v[242:243], v180 offset:14336
	v_fmamk_f32 v87, v87, 0x3dd53b94, v194
	v_exp_f32_e32 v230, v85
	v_fmamk_f32 v154, v72, 0x3dd53b94, v194
	v_fmamk_f32 v155, v73, 0x3dd53b94, v194
	v_fmamk_f32 v152, v74, 0x3dd53b94, v194
	v_mfma_f32_32x32x16_bf16 v[48:63], v[156:159], v[248:251], v[48:63]
	ds_read_b64_tr_b16 v[248:249], v180 offset:12800
	ds_read_b64_tr_b16 v[250:251], v180 offset:14848
	v_fmamk_f32 v153, v75, 0x3dd53b94, v194
	v_fmamk_f32 v88, v88, 0x3dd53b94, v194
	v_exp_f32_e32 v223, v86
	v_fmamk_f32 v89, v89, 0x3dd53b94, v194
	s_waitcnt lgkmcnt(4)
	v_mfma_f32_32x32x16_bf16 v[16:31], v[156:159], v[232:235], v[16:31]
	ds_read_b64_tr_b16 v[232:233], v180 offset:13312
	ds_read_b64_tr_b16 v[234:235], v180 offset:15360
	v_exp_f32_e32 v224, v87
	v_fmamk_f32 v90, v90, 0x3dd53b94, v194
	v_exp_f32_e32 v219, v88
	v_fmamk_f32 v91, v91, 0x3dd53b94, v194
	v_mfma_f32_32x32x16_bf16 v[0:15], v[156:159], v[236:239], v[0:15]
	ds_read_b64_tr_b16 v[236:237], v180 offset:13824
	ds_read_b64_tr_b16 v[238:239], v180 offset:15872
	v_exp_f32_e32 v221, v89
	v_fmamk_f32 v92, v92, 0x3dd53b94, v194
	v_exp_f32_e32 v220, v90
	v_fmamk_f32 v158, v68, 0x3dd53b94, v194
	s_waitcnt lgkmcnt(4)
	v_mfma_f32_32x32x16_bf16 v[32:47], v[160:163], v[240:243], v[32:47]
	v_fmamk_f32 v159, v69, 0x3dd53b94, v194
	v_fmamk_f32 v156, v70, 0x3dd53b94, v194
	v_fmamk_f32 v157, v71, 0x3dd53b94, v194
	v_fmamk_f32 v93, v93, 0x3dd53b94, v194
	v_exp_f32_e32 v222, v91
	v_mfma_f32_32x32x16_bf16 v[48:63], v[160:163], v[248:251], v[48:63]
	v_fmamk_f32 v94, v94, 0x3dd53b94, v194
	v_exp_f32_e32 v215, v92
	v_fmamk_f32 v95, v95, 0x3dd53b94, v194
	v_exp_f32_e32 v217, v93
	s_waitcnt lgkmcnt(0)
	v_mfma_f32_32x32x16_bf16 v[16:31], v[160:163], v[232:235], v[16:31]
	v_exp_f32_e32 v216, v94
	v_exp_f32_e32 v218, v95
	v_mfma_f32_32x32x16_bf16 v[0:15], v[160:163], v[236:239], v[0:15]
	v_fmamk_f32 v162, v64, 0x3dd53b94, v194
	v_fmamk_f32 v163, v65, 0x3dd53b94, v194
	v_fmamk_f32 v160, v66, 0x3dd53b94, v194
	v_fmamk_f32 v161, v67, 0x3dd53b94, v194
	v_cmp_gt_f32_e32 vcc, 1.0, v214
	s_cbranch_vccz .Lattn_skip_rs1
; __device__ __forceinline__ void qkt(f32x16& p0, f32x16& p1, const char* Ks, const bf16x8* qr, const char* qrl, int r32, int hi) {
;   p0 = f32x16{}; p1 = f32x16{};
; #pragma unroll
;   for (int d0 = 0; d0 < 8; ++d0) { int cb = (d0 * 16 + hi * 8) * 2;
;     bf16x8 b0 = *reinterpret_cast<const bf16x8*>(Ks + KSWZ(r32, cb));
;     bf16x8 b1 = *reinterpret_cast<const bf16x8*>(Ks + KSWZ(32 + r32, cb));
;     p0 = __builtin_amdgcn_mfma_f32_32x32x16_bf16(b0, qr[d0], p0, 0, 0, 0);
;     p1 = __builtin_amdgcn_mfma_f32_32x32x16_bf16(b1, qr[d0], p1, 0, 0, 0); }
; #pragma unroll
;   for (int d0 = 8; d0 < 12; ++d0) { int cb = (d0 * 16 + hi * 8) * 2;
;     bf16x8 b0 = *reinterpret_cast<const bf16x8*>(Ks + KSWZ(r32, cb));
;     bf16x8 b1 = *reinterpret_cast<const bf16x8*>(Ks + KSWZ(32 + r32, cb));
;     bf16x8 qf = *reinterpret_cast<const bf16x8*>(qrl + (((2 * (d0 - 8) + hi) ^ ((r32 >> 1) & 7)) << 4));
;     p0 = __builtin_amdgcn_mfma_f32_32x32x16_bf16(b0, qf, p0, 0, 0, 0);
;     p1 = __builtin_amdgcn_mfma_f32_32x32x16_bf16(b1, qf, p1, 0, 0, 0); }
	s_and_saveexec_b64 s[18:19], s[38:39]
	ds_write_b32 v175, v214 offset:128
	s_or_b64 exec, exec, s[18:19]
	s_waitcnt lgkmcnt(0)
	v_add_u32_e32 v194, v173, v164
	ds_read_b128 v[232:235], v194 offset:224
	ds_read_b128 v[236:239], v194 offset:192
	ds_read_b128 v[240:243], v194 offset:160
	ds_read_b128 v[248:251], v194 offset:128
	s_waitcnt lgkmcnt(0)
	v_pk_mul_f32 v[44:45], v[44:45], v[232:233]
	v_pk_mul_f32 v[46:47], v[46:47], v[234:235]
	v_pk_mul_f32 v[40:41], v[40:41], v[236:237]
	v_pk_mul_f32 v[42:43], v[42:43], v[238:239]
	v_pk_mul_f32 v[36:37], v[36:37], v[240:241]
	v_pk_mul_f32 v[38:39], v[38:39], v[242:243]
	v_pk_mul_f32 v[32:33], v[32:33], v[248:249]
	v_pk_mul_f32 v[34:35], v[34:35], v[250:251]
	v_pk_mul_f32 v[60:61], v[60:61], v[232:233]
	v_pk_mul_f32 v[62:63], v[62:63], v[234:235]
	v_pk_mul_f32 v[56:57], v[56:57], v[236:237]
	v_pk_mul_f32 v[58:59], v[58:59], v[238:239]
	v_pk_mul_f32 v[52:53], v[52:53], v[240:241]
	v_pk_mul_f32 v[54:55], v[54:55], v[242:243]
	v_pk_mul_f32 v[48:49], v[48:49], v[248:249]
	v_pk_mul_f32 v[50:51], v[50:51], v[250:251]
	v_pk_mul_f32 v[28:29], v[28:29], v[232:233]
	v_pk_mul_f32 v[30:31], v[30:31], v[234:235]
	v_pk_mul_f32 v[24:25], v[24:25], v[236:237]
	v_pk_mul_f32 v[26:27], v[26:27], v[238:239]
	v_pk_mul_f32 v[20:21], v[20:21], v[240:241]
	v_pk_mul_f32 v[22:23], v[22:23], v[242:243]
	v_pk_mul_f32 v[16:17], v[16:17], v[248:249]
	v_pk_mul_f32 v[18:19], v[18:19], v[250:251]
	v_pk_mul_f32 v[12:13], v[12:13], v[232:233]
	v_pk_mul_f32 v[14:15], v[14:15], v[234:235]
	v_pk_mul_f32 v[8:9], v[8:9], v[236:237]
	v_pk_mul_f32 v[10:11], v[10:11], v[238:239]
	v_pk_mul_f32 v[4:5], v[4:5], v[240:241]
	v_pk_mul_f32 v[6:7], v[6:7], v[242:243]
	v_pk_mul_f32 v[0:1], v[0:1], v[248:249]
	v_pk_mul_f32 v[2:3], v[2:3], v[250:251]
.Lattn_skip_rs1:
	s_waitcnt lgkmcnt(0)
	s_barrier
	ds_read_b128 v[64:67], v199 offset:12288
	ds_read_b128 v[68:71], v199 offset:24576
	ds_read_b128 v[232:235], v205 offset:12288
	ds_read_b128 v[236:239], v205 offset:24576
	ds_read_b128 v[240:243], v206 offset:12288
	ds_read_b128 v[248:251], v206 offset:24576
	v_exp_f32_e32 v162, v162
	v_add_f32_e32 v211, v225, v228
	v_exp_f32_e32 v163, v163
	v_add_f32_e32 v211, v226, v211
	v_exp_f32_e32 v160, v160
	s_waitcnt lgkmcnt(4)
	v_mfma_f32_32x32x16_bf16 v[80:95], v[64:67], v[124:127], 0
	v_add_f32_e32 v211, v229, v211
	v_exp_f32_e32 v161, v161
	v_add_f32_e32 v211, v227, v211
	v_mfma_f32_32x32x16_bf16 v[64:79], v[68:71], v[124:127], 0
	v_exp_f32_e32 v158, v158
	v_add_f32_e32 v211, v230, v211
	s_waitcnt lgkmcnt(2)
	v_mfma_f32_32x32x16_bf16 v[80:95], v[232:235], v[120:123], v[80:95]
	ds_read_b128 v[232:235], v208 offset:12288
	v_exp_f32_e32 v159, v159
	v_add_f32_e32 v211, v223, v211
	v_mfma_f32_32x32x16_bf16 v[64:79], v[236:239], v[120:123], v[64:79]
	ds_read_b128 v[236:239], v208 offset:24576
	v_exp_f32_e32 v156, v156
	v_add_f32_e32 v211, v224, v211
	s_waitcnt lgkmcnt(2)
	v_mfma_f32_32x32x16_bf16 v[80:95], v[240:243], v[116:119], v[80:95]
	ds_read_b128 v[240:243], v207 offset:12288
	v_exp_f32_e32 v157, v157
	v_add_f32_e32 v211, v219, v211
	v_mfma_f32_32x32x16_bf16 v[64:79], v[248:251], v[116:119], v[64:79]
	ds_read_b128 v[248:251], v207 offset:24576
	v_exp_f32_e32 v154, v154
	v_add_f32_e32 v211, v221, v211
	s_waitcnt lgkmcnt(2)
	v_mfma_f32_32x32x16_bf16 v[80:95], v[232:235], v[112:115], v[80:95]
	ds_read_b128 v[232:235], v204 offset:12288
	v_exp_f32_e32 v155, v155
	v_add_f32_e32 v211, v220, v211
	v_mfma_f32_32x32x16_bf16 v[64:79], v[236:239], v[112:115], v[64:79]
	ds_read_b128 v[236:239], v204 offset:24576
	v_exp_f32_e32 v152, v152
	v_add_f32_e32 v211, v222, v211
	s_waitcnt lgkmcnt(2)
	v_mfma_f32_32x32x16_bf16 v[80:95], v[240:243], v[108:111], v[80:95]
	ds_read_b128 v[240:243], v203 offset:12288
	v_exp_f32_e32 v153, v153
	v_add_f32_e32 v211, v215, v211
	v_mfma_f32_32x32x16_bf16 v[64:79], v[248:251], v[108:111], v[64:79]
	ds_read_b128 v[248:251], v203 offset:24576
	v_exp_f32_e32 v150, v150
	v_add_f32_e32 v211, v217, v211
	s_waitcnt lgkmcnt(2)
	v_mfma_f32_32x32x16_bf16 v[80:95], v[232:235], v[104:107], v[80:95]
	ds_read_b128 v[232:235], v200 offset:12288
	v_exp_f32_e32 v151, v151
	v_add_f32_e32 v211, v216, v211
	v_mfma_f32_32x32x16_bf16 v[64:79], v[236:239], v[104:107], v[64:79]
	ds_read_b128 v[236:239], v200 offset:24576
	v_exp_f32_e32 v148, v148
	v_add_f32_e32 v211, v218, v211
	s_waitcnt lgkmcnt(2)
	v_mfma_f32_32x32x16_bf16 v[80:95], v[240:243], v[100:103], v[80:95]
	ds_read_b128 v[240:243], v191 offset:12288
	v_exp_f32_e32 v149, v149
	v_add_f32_e32 v212, v162, v163
	v_add_f32_e32 v212, v160, v212
	v_mfma_f32_32x32x16_bf16 v[64:79], v[248:251], v[100:103], v[64:79]
	ds_read_b128 v[248:251], v202 offset:24576
	v_add_f32_e32 v212, v161, v212
	v_add_f32_e32 v212, v158, v212
	v_add_f32_e32 v212, v159, v212
	v_add_f32_e32 v212, v156, v212
	s_waitcnt lgkmcnt(2)
	v_mfma_f32_32x32x16_bf16 v[80:95], v[232:235], v[96:99], v[80:95]
	ds_read_b128 v[232:235], v182
	v_add_f32_e32 v212, v157, v212
	v_add_f32_e32 v212, v154, v212
	v_add_f32_e32 v212, v155, v212
	v_add_f32_e32 v212, v152, v212
	v_mfma_f32_32x32x16_bf16 v[64:79], v[236:239], v[96:99], v[64:79]
	ds_read_b128 v[236:239], v198 offset:12288
	v_add_f32_e32 v212, v153, v212
	v_add_f32_e32 v212, v150, v212
	v_add_f32_e32 v212, v151, v212
	v_add_f32_e32 v212, v148, v212
	s_waitcnt lgkmcnt(1)
	v_mfma_f32_32x32x16_bf16 v[80:95], v[240:243], v[232:235], v[80:95]
	ds_read_b128 v[240:243], v201 offset:24576
	v_add_f32_e32 v212, v149, v212
	v_add_f32_e32 v211, v211, v212
	v_mov_b32_e32 v212, v211
	v_cvt_pk_bf16_f32 v158, v158, v159
	v_mfma_f32_32x32x16_bf16 v[64:79], v[248:251], v[232:235], v[64:79]
	ds_read_b128 v[248:251], v181
	ds_read_b128 v[232:235], v187 offset:12288
	v_cvt_pk_bf16_f32 v159, v156, v157
	v_permlane32_swap_b32_e32 v211, v212
	v_cvt_pk_bf16_f32 v156, v162, v163
	v_cvt_pk_bf16_f32 v157, v160, v161
	s_waitcnt lgkmcnt(1)
; #define SBAR() __builtin_amdgcn_sched_barrier(0)
; __device__ __forceinline__ void qkt(f32x16& p0, f32x16& p1, const char* Ks, const bf16x8* qr, const char* qrl, int r32, int hi) {
;   p0 = f32x16{}; p1 = f32x16{};
; #pragma unroll
;   for (int d0 = 0; d0 < 8; ++d0) { int cb = (d0 * 16 + hi * 8) * 2;
;     bf16x8 b0 = *reinterpret_cast<const bf16x8*>(Ks + KSWZ(r32, cb));
;     bf16x8 b1 = *reinterpret_cast<const bf16x8*>(Ks + KSWZ(32 + r32, cb));
;     p0 = __builtin_amdgcn_mfma_f32_32x32x16_bf16(b0, qr[d0], p0, 0, 0, 0);
;     p1 = __builtin_amdgcn_mfma_f32_32x32x16_bf16(b1, qr[d0], p1, 0, 0, 0); }
; #pragma unroll
;   for (int d0 = 8; d0 < 12; ++d0) { int cb = (d0 * 16 + hi * 8) * 2;
;     bf16x8 b0 = *reinterpret_cast<const bf16x8*>(Ks + KSWZ(r32, cb));
;     bf16x8 b1 = *reinterpret_cast<const bf16x8*>(Ks + KSWZ(32 + r32, cb));
;     bf16x8 qf = *reinterpret_cast<const bf16x8*>(qrl + (((2 * (d0 - 8) + hi) ^ ((r32 >> 1) & 7)) << 4));
;     p0 = __builtin_amdgcn_mfma_f32_32x32x16_bf16(b0, qf, p0, 0, 0, 0);
;     p1 = __builtin_amdgcn_mfma_f32_32x32x16_bf16(b1, qf, p1, 0, 0, 0); }
; __device__ __forceinline__ void attn_unit(const bf16_t* __restrict__ Qb, const bf16_t* __restrict__ Kn, const bf16_t* __restrict__ Vh, const bf16_t* __restrict__ Kr,
;                                           bf16_t* GO, int seq, char* lds, const int tid) {
;     ...
;     SWRITE(bp, 0); if (j + 3 < NT) SLOAD(0, (j + 3) * KVBLK); SBAR();
;     pv_d0(o, vb0 + bc * SHM_V, pa0, pa1, pa2, pa3); partialSM(pA0, pA1, m_reg, mnA, alA);
	v_mfma_f32_32x32x16_bf16 v[80:95], v[236:239], v[248:251], v[80:95]
	ds_read_b128 v[236:239], v189 offset:24576
	v_cvt_pk_bf16_f32 v160, v154, v155
	v_cvt_pk_bf16_f32 v161, v152, v153
	v_cvt_pk_bf16_f32 v162, v150, v151
	v_cvt_pk_bf16_f32 v163, v148, v149
	v_mfma_f32_32x32x16_bf16 v[64:79], v[240:243], v[248:251], v[64:79]
	ds_read_b128 v[240:243], v179
	ds_read_b128 v[248:251], v188 offset:12288
	v_add_f32_e32 v211, v211, v212
	v_cvt_pk_bf16_f32 v148, v225, v228
	v_cvt_pk_bf16_f32 v149, v226, v229
	v_cvt_pk_bf16_f32 v150, v227, v230
	s_waitcnt lgkmcnt(1)
	v_mfma_f32_32x32x16_bf16 v[80:95], v[232:235], v[240:243], v[80:95]
	ds_read_b128 v[232:235], v190 offset:24576
	v_cvt_pk_bf16_f32 v151, v223, v224
	v_cvt_pk_bf16_f32 v152, v219, v221
	v_cvt_pk_bf16_f32 v153, v220, v222
	v_cvt_pk_bf16_f32 v154, v215, v217
	v_mfma_f32_32x32x16_bf16 v[64:79], v[236:239], v[240:243], v[64:79]
	ds_read_b128 v[236:239], v177
	v_cvt_pk_bf16_f32 v155, v216, v218
	v_fma_f32 v176, v214, v176, v211
	s_nop 1
	v_permlane32_swap_b32_e32 v156, v158
	s_waitcnt lgkmcnt(0)
	v_mfma_f32_32x32x16_bf16 v[80:95], v[248:251], v[236:239], v[80:95]
	v_permlane32_swap_b32_e32 v157, v159
	v_permlane32_swap_b32_e32 v160, v162
	v_permlane32_swap_b32_e32 v161, v163
	v_permlane32_swap_b32_e32 v148, v150
	v_mfma_f32_32x32x16_bf16 v[64:79], v[232:235], v[236:239], v[64:79]
	v_permlane32_swap_b32_e32 v149, v151
	v_permlane32_swap_b32_e32 v152, v154
	v_permlane32_swap_b32_e32 v153, v155
	v_lshl_add_u32 v231, s76, 14, v178
	ds_read_b64_tr_b16 v[240:241], v231 offset:0
	ds_read_b64_tr_b16 v[242:243], v231 offset:2048
	ds_read_b64_tr_b16 v[248:249], v231 offset:512
	ds_read_b64_tr_b16 v[250:251], v231 offset:2560
	ds_read_b64_tr_b16 v[232:233], v231 offset:1024
	ds_read_b64_tr_b16 v[234:235], v231 offset:3072
	ds_read_b64_tr_b16 v[236:237], v231 offset:1536
	ds_read_b64_tr_b16 v[238:239], v231 offset:3584
	v_add_u32_e32 v194, s31, v183
	s_waitcnt vmcnt(4)
	ds_write_b128 v194, v[140:143]
	v_add_u32_e32 v194, s31, v184
	s_add_i32 s73, s73, 2
	s_cmp_ge_u32 s73, s45
	s_waitcnt vmcnt(2)
	ds_write_b128 v194, v[144:147]
	s_cselect_b64 s[28:29], -1, 0
	ds_write_b128 v185, v[136:139] offset:36864
	s_waitcnt vmcnt(1)
	ds_write_b128 v185, v[132:135] offset:49152
	s_and_b64 vcc, exec, s[28:29]
	s_waitcnt vmcnt(0)
	ds_write_b128 v186, v[128:131] offset:36864
	s_cbranch_vccnz .LBB0_1157
	v_add_co_u32_e32 v128, vcc, 0xfffe0000, v168
	s_nop 1
	v_addc_co_u32_e32 v129, vcc, -1, v169, vcc
	global_load_dwordx4 v[140:143], v[128:129], off
	global_load_dwordx4 v[136:139], v[128:129], off offset:-256
	global_load_dwordx4 v[144:147], v[168:169], off
	global_load_dwordx4 v[132:135], v[168:169], off offset:-256
	s_nop 0
	global_load_dwordx4 v[128:131], v[166:167], off
.LBB0_1157:
	v_max3_f32 v194, v80, v81, v82
	v_max3_f32 v195, v64, v65, v66
	v_max3_f32 v194, v194, v83, v84
	v_max3_f32 v195, v195, v67, v68
	v_max3_f32 v194, v194, v85, v86
	v_max3_f32 v195, v195, v69, v70
	s_waitcnt lgkmcnt(9)
	v_mfma_f32_32x32x16_bf16 v[32:47], v[148:151], v[240:243], v[32:47]
	ds_read_b64_tr_b16 v[240:241], v231 offset:4096
	ds_read_b64_tr_b16 v[242:243], v231 offset:6144
	v_max3_f32 v194, v194, v87, v88
	v_max3_f32 v195, v195, v71, v72
	v_max3_f32 v194, v194, v89, v90
	v_max3_f32 v195, v195, v73, v74
	v_max3_f32 v194, v194, v91, v92
	v_max3_f32 v195, v195, v75, v76
	v_mfma_f32_32x32x16_bf16 v[48:63], v[148:151], v[248:251], v[48:63]
	ds_read_b64_tr_b16 v[248:249], v231 offset:4608
	ds_read_b64_tr_b16 v[250:251], v231 offset:6656
	v_max3_f32 v194, v194, v93, v94
	v_max3_f32 v195, v195, v77, v78
	v_max3_f32 v194, v194, v95, v195
	v_max_f32_e32 v194, v194, v79
	v_mov_b32_e32 v195, v194
	s_nop 1
	s_waitcnt lgkmcnt(9)
	v_mfma_f32_32x32x16_bf16 v[16:31], v[148:151], v[232:235], v[16:31]
	ds_read_b64_tr_b16 v[232:233], v231 offset:5120
	ds_read_b64_tr_b16 v[234:235], v231 offset:7168
	v_permlane32_swap_b32_e32 v194, v195
	v_max_f32_e32 v194, v194, v195
	v_sub_f32_e32 v195, v194, v210
	v_cmp_ge_f32_e32 vcc, s15, v195
	v_max_f32_e32 v194, v210, v194
	v_sub_f32_e32 v195, v210, v194
	v_mfma_f32_32x32x16_bf16 v[0:15], v[148:151], v[236:239], v[0:15]
	ds_read_b64_tr_b16 v[236:237], v231 offset:5632
	ds_read_b64_tr_b16 v[238:239], v231 offset:7680
	v_mul_f32_e32 v195, 0x3dd53b94, v195
	v_exp_f32_e32 v195, v195
	s_cmp_eq_u64 vcc, exec
	s_cselect_b64 s[40:41], -1, 0
	v_cndmask_b32_e64 v213, v195, 1.0, s[40:41]
	s_waitcnt lgkmcnt(4)
	v_mfma_f32_32x32x16_bf16 v[32:47], v[152:155], v[240:243], v[32:47]
	ds_read_b64_tr_b16 v[240:241], v231 offset:8192
	ds_read_b64_tr_b16 v[242:243], v231 offset:10240
	v_cndmask_b32_e64 v210, v194, v210, s[40:41]
	v_mul_f32_e32 v194, 0xbdd53b94, v210
	v_fmamk_f32 v80, v80, 0x3dd53b94, v194
	v_fmamk_f32 v81, v81, 0x3dd53b94, v194
	v_fmamk_f32 v82, v82, 0x3dd53b94, v194
	v_mfma_f32_32x32x16_bf16 v[48:63], v[152:155], v[248:251], v[48:63]
	ds_read_b64_tr_b16 v[248:249], v231 offset:8704
	ds_read_b64_tr_b16 v[250:251], v231 offset:10752
	v_exp_f32_e32 v225, v80
	v_fmamk_f32 v83, v83, 0x3dd53b94, v194
	v_exp_f32_e32 v228, v81
	v_fmamk_f32 v150, v76, 0x3dd53b94, v194
	s_waitcnt lgkmcnt(4)
	v_mfma_f32_32x32x16_bf16 v[16:31], v[152:155], v[232:235], v[16:31]
	ds_read_b64_tr_b16 v[232:233], v231 offset:9216
	ds_read_b64_tr_b16 v[234:235], v231 offset:11264
	v_fmamk_f32 v151, v77, 0x3dd53b94, v194
	v_fmamk_f32 v148, v78, 0x3dd53b94, v194
	v_fmamk_f32 v149, v79, 0x3dd53b94, v194
	v_fmamk_f32 v84, v84, 0x3dd53b94, v194
	v_exp_f32_e32 v226, v82
	v_mfma_f32_32x32x16_bf16 v[0:15], v[152:155], v[236:239], v[0:15]
	ds_read_b64_tr_b16 v[236:237], v231 offset:9728
	ds_read_b64_tr_b16 v[238:239], v231 offset:11776
	v_fmamk_f32 v85, v85, 0x3dd53b94, v194
	v_exp_f32_e32 v229, v83
	v_fmamk_f32 v86, v86, 0x3dd53b94, v194
	v_exp_f32_e32 v227, v84
	s_waitcnt lgkmcnt(4)
; #define SBAR() __builtin_amdgcn_sched_barrier(0)
; template <int D0> __device__ __forceinline__ void pv_one(f32x16& od, int vb, bf16x8 pa0, bf16x8 pa1, bf16x8 pa2, bf16x8 pa3) {
;   const s16x4 l0 = tr_read<v_rd_off(D0, 0, 0)>(vb), h0 = tr_read<v_rd_off(D0, 0, 1)>(vb), l1 = tr_read<v_rd_off(D0, 1, 0)>(vb), h1 = tr_read<v_rd_off(D0, 1, 1)>(vb);
;   const s16x4 l2 = tr_read<v_rd_off(D0, 2, 0)>(vb), h2 = tr_read<v_rd_off(D0, 2, 1)>(vb), l3 = tr_read<v_rd_off(D0, 3, 0)>(vb), h3 = tr_read<v_rd_off(D0, 3, 1)>(vb);
;   asm volatile("s_waitcnt lgkmcnt(0)" ::: "memory"); SBAR();
;     ...
;   od = __builtin_amdgcn_mfma_f32_32x32x16_bf16(pa0, PK(l0, h0), od, 0, 0, 0);
;   od = __builtin_amdgcn_mfma_f32_32x32x16_bf16(pa1, PK(l1, h1), od, 0, 0, 0);
;   od = __builtin_amdgcn_mfma_f32_32x32x16_bf16(pa2, PK(l2, h2), od, 0, 0, 0);
;   od = __builtin_amdgcn_mfma_f32_32x32x16_bf16(pa3, PK(l3, h3), od, 0, 0, 0);
;     ...
; }
; __device__ __forceinline__ void pv_d0(f32x16* o, int vb, bf16x8 pa0, bf16x8 pa1, bf16x8 pa2, bf16x8 pa3) {
;   pv_one<0>(o[0], vb, pa0, pa1, pa2, pa3); pv_one<1>(o[1], vb, pa0, pa1, pa2, pa3); pv_one<2>(o[2], vb, pa0, pa1, pa2, pa3); pv_one<3>(o[3], vb, pa0, pa1, pa2, pa3);
	v_mfma_f32_32x32x16_bf16 v[32:47], v[156:159], v[240:243], v[32:47]
	ds_read_b64_tr_b16 v[240:241], v231 offset:12288
	ds_read_b64_tr_b16 v[242:243], v231 offset:14336
	v_fmamk_f32 v87, v87, 0x3dd53b94, v194
	v_exp_f32_e32 v230, v85
	v_fmamk_f32 v154, v72, 0x3dd53b94, v194
	v_fmamk_f32 v155, v73, 0x3dd53b94, v194
	v_fmamk_f32 v152, v74, 0x3dd53b94, v194
	v_mfma_f32_32x32x16_bf16 v[48:63], v[156:159], v[248:251], v[48:63]
	ds_read_b64_tr_b16 v[248:249], v231 offset:12800
	ds_read_b64_tr_b16 v[250:251], v231 offset:14848
	v_fmamk_f32 v153, v75, 0x3dd53b94, v194
	v_fmamk_f32 v88, v88, 0x3dd53b94, v194
	v_exp_f32_e32 v223, v86
	v_fmamk_f32 v89, v89, 0x3dd53b94, v194
	s_waitcnt lgkmcnt(4)
	v_mfma_f32_32x32x16_bf16 v[16:31], v[156:159], v[232:235], v[16:31]
	ds_read_b64_tr_b16 v[232:233], v231 offset:13312
	ds_read_b64_tr_b16 v[234:235], v231 offset:15360
	v_exp_f32_e32 v224, v87
	v_fmamk_f32 v90, v90, 0x3dd53b94, v194
	v_exp_f32_e32 v219, v88
	v_fmamk_f32 v91, v91, 0x3dd53b94, v194
	v_mfma_f32_32x32x16_bf16 v[0:15], v[156:159], v[236:239], v[0:15]
	ds_read_b64_tr_b16 v[236:237], v231 offset:13824
	ds_read_b64_tr_b16 v[238:239], v231 offset:15872
	v_exp_f32_e32 v221, v89
	v_fmamk_f32 v92, v92, 0x3dd53b94, v194
	v_exp_f32_e32 v220, v90
	v_fmamk_f32 v158, v68, 0x3dd53b94, v194
	s_waitcnt lgkmcnt(4)
	v_mfma_f32_32x32x16_bf16 v[32:47], v[160:163], v[240:243], v[32:47]
	v_fmamk_f32 v159, v69, 0x3dd53b94, v194
	v_fmamk_f32 v156, v70, 0x3dd53b94, v194
	v_fmamk_f32 v157, v71, 0x3dd53b94, v194
	v_fmamk_f32 v93, v93, 0x3dd53b94, v194
	v_exp_f32_e32 v222, v91
	v_mfma_f32_32x32x16_bf16 v[48:63], v[160:163], v[248:251], v[48:63]
	v_fmamk_f32 v94, v94, 0x3dd53b94, v194
	v_exp_f32_e32 v215, v92
	v_fmamk_f32 v95, v95, 0x3dd53b94, v194
	v_exp_f32_e32 v217, v93
	s_waitcnt lgkmcnt(0)
	v_mfma_f32_32x32x16_bf16 v[16:31], v[160:163], v[232:235], v[16:31]
	v_exp_f32_e32 v216, v94
	v_exp_f32_e32 v218, v95
	v_mfma_f32_32x32x16_bf16 v[0:15], v[160:163], v[236:239], v[0:15]
	v_fmamk_f32 v162, v64, 0x3dd53b94, v194
	v_fmamk_f32 v163, v65, 0x3dd53b94, v194
	v_fmamk_f32 v160, v66, 0x3dd53b94, v194
	v_fmamk_f32 v161, v67, 0x3dd53b94, v194
	v_cmp_gt_f32_e32 vcc, 1.0, v213
	s_cbranch_vccz .Lattn_skip_rs2
	s_and_saveexec_b64 s[18:19], s[38:39]
	ds_write_b32 v175, v213 offset:128
	s_or_b64 exec, exec, s[18:19]
	s_waitcnt lgkmcnt(0)
	v_add_u32_e32 v194, v173, v164
	ds_read_b128 v[232:235], v194 offset:224
	ds_read_b128 v[236:239], v194 offset:192
	ds_read_b128 v[240:243], v194 offset:160
	ds_read_b128 v[248:251], v194 offset:128
	s_waitcnt lgkmcnt(0)
	v_pk_mul_f32 v[44:45], v[44:45], v[232:233]
	v_pk_mul_f32 v[46:47], v[46:47], v[234:235]
	v_pk_mul_f32 v[40:41], v[40:41], v[236:237]
	v_pk_mul_f32 v[42:43], v[42:43], v[238:239]
	v_pk_mul_f32 v[36:37], v[36:37], v[240:241]
	v_pk_mul_f32 v[38:39], v[38:39], v[242:243]
	v_pk_mul_f32 v[32:33], v[32:33], v[248:249]
	v_pk_mul_f32 v[34:35], v[34:35], v[250:251]
	v_pk_mul_f32 v[60:61], v[60:61], v[232:233]
	v_pk_mul_f32 v[62:63], v[62:63], v[234:235]
	v_pk_mul_f32 v[56:57], v[56:57], v[236:237]
	v_pk_mul_f32 v[58:59], v[58:59], v[238:239]
	v_pk_mul_f32 v[52:53], v[52:53], v[240:241]
	v_pk_mul_f32 v[54:55], v[54:55], v[242:243]
	v_pk_mul_f32 v[48:49], v[48:49], v[248:249]
	v_pk_mul_f32 v[50:51], v[50:51], v[250:251]
	v_pk_mul_f32 v[28:29], v[28:29], v[232:233]
	v_pk_mul_f32 v[30:31], v[30:31], v[234:235]
	v_pk_mul_f32 v[24:25], v[24:25], v[236:237]
	v_pk_mul_f32 v[26:27], v[26:27], v[238:239]
	v_pk_mul_f32 v[20:21], v[20:21], v[240:241]
	v_pk_mul_f32 v[22:23], v[22:23], v[242:243]
	v_pk_mul_f32 v[16:17], v[16:17], v[248:249]
	v_pk_mul_f32 v[18:19], v[18:19], v[250:251]
	v_pk_mul_f32 v[12:13], v[12:13], v[232:233]
	v_pk_mul_f32 v[14:15], v[14:15], v[234:235]
	v_pk_mul_f32 v[8:9], v[8:9], v[236:237]
	v_pk_mul_f32 v[10:11], v[10:11], v[238:239]
	v_pk_mul_f32 v[4:5], v[4:5], v[240:241]
	v_pk_mul_f32 v[6:7], v[6:7], v[242:243]
	v_pk_mul_f32 v[0:1], v[0:1], v[248:249]
	v_pk_mul_f32 v[2:3], v[2:3], v[250:251]
.Lattn_skip_rs2:
	s_waitcnt lgkmcnt(0)
	s_barrier
	s_movk_i32 s34, 0x6000
	s_mov_b64 s[18:19], 0x4000
	v_lshl_add_u64 v[166:167], v[166:167], 0, s[18:19]
	v_lshl_add_u64 v[168:169], v[168:169], 0, s[10:11]
	s_and_b64 vcc, exec, s[28:29]
	s_cbranch_vccnz .LBB0_1163
	s_mov_b32 s76, s30
	v_mov_b32_e32 v209, v213
	s_branch .LBB0_1151
; #define SBAR() __builtin_amdgcn_sched_barrier(0)
; __device__ __forceinline__ void qkt(f32x16& p0, f32x16& p1, const char* Ks, const bf16x8* qr, const char* qrl, int r32, int hi) {
;   p0 = f32x16{}; p1 = f32x16{};
; #pragma unroll
;   for (int d0 = 0; d0 < 8; ++d0) { int cb = (d0 * 16 + hi * 8) * 2;
;     bf16x8 b0 = *reinterpret_cast<const bf16x8*>(Ks + KSWZ(r32, cb));
;     bf16x8 b1 = *reinterpret_cast<const bf16x8*>(Ks + KSWZ(32 + r32, cb));
;     p0 = __builtin_amdgcn_mfma_f32_32x32x16_bf16(b0, qr[d0], p0, 0, 0, 0);
;     p1 = __builtin_amdgcn_mfma_f32_32x32x16_bf16(b1, qr[d0], p1, 0, 0, 0); }
; #pragma unroll
;   for (int d0 = 8; d0 < 12; ++d0) { int cb = (d0 * 16 + hi * 8) * 2;
;     bf16x8 b0 = *reinterpret_cast<const bf16x8*>(Ks + KSWZ(r32, cb));
;     bf16x8 b1 = *reinterpret_cast<const bf16x8*>(Ks + KSWZ(32 + r32, cb));
;     bf16x8 qf = *reinterpret_cast<const bf16x8*>(qrl + (((2 * (d0 - 8) + hi) ^ ((r32 >> 1) & 7)) << 4));
;     p0 = __builtin_amdgcn_mfma_f32_32x32x16_bf16(b0, qf, p0, 0, 0, 0);
;     p1 = __builtin_amdgcn_mfma_f32_32x32x16_bf16(b1, qf, p1, 0, 0, 0); }
; __device__ __forceinline__ void attn_unit(const bf16_t* __restrict__ Qb, const bf16_t* __restrict__ Kn, const bf16_t* __restrict__ Vh, const bf16_t* __restrict__ Kr,
;                                           bf16_t* GO, int seq, char* lds, const int tid) {
;     ...
;   { const int bp = bc == 0 ? 2 : bc - 1;
;     SBAR(); qkt(pB0, pB1, K_lds + bc * SHM_K, qr, qrl, r32, hi);
;     finishSM(pA0, pA1, alA, l_reg, pa0, pa1, pa2, pa3); SBAR();
;     pv_d0(o, vb0 + bp * SHM_V, pa0, pa1, pa2, pa3); partialSM(pB0, pB1, m_reg, mnB, alB);
.LBB0_1163:
	v_add_u32_e32 v199, 0xffff7000, v199
	v_add_u32_e32 v205, 0xffff7000, v205
	v_add_u32_e32 v206, 0xffff7000, v206
	v_add_u32_e32 v208, 0xffff7000, v208
	v_add_u32_e32 v207, 0xffff7000, v207
	v_add_u32_e32 v204, 0xffff7000, v204
	v_add_u32_e32 v203, 0xffff7000, v203
	v_add_u32_e32 v200, 0xffff7000, v200
	v_add_u32_e32 v191, 0xffff7000, v191
	v_add_u32_e32 v198, 0xffff7000, v198
	v_add_u32_e32 v187, 0xffff7000, v187
	v_add_u32_e32 v188, 0xffff7000, v188
	v_add_u32_e32 v202, 0xffff7000, v202
	v_add_u32_e32 v201, 0xffff7000, v201
	v_add_u32_e32 v189, 0xffff7000, v189
	v_add_u32_e32 v190, 0xffff7000, v190
	v_add_u32_e32 v185, 0xffff7000, v185
	v_add_u32_e32 v186, 0xffff7000, v186
	v_add_u32_e32 v68, s34, v199
	ds_read_b128 v[64:67], v68 offset:49152
	ds_read_b128 v[68:71], v68 offset:61440
	s_waitcnt vmcnt(0)
	v_add_u32_e32 v128, s34, v205
	s_waitcnt lgkmcnt(1)
	v_mfma_f32_32x32x16_bf16 v[80:95], v[64:67], v[124:127], 0
	s_waitcnt lgkmcnt(0)
	v_mfma_f32_32x32x16_bf16 v[64:79], v[68:71], v[124:127], 0
	ds_read_b128 v[124:127], v128 offset:49152
	ds_read_b128 v[128:131], v128 offset:61440
	s_waitcnt lgkmcnt(1)
	v_mfma_f32_32x32x16_bf16 v[80:95], v[124:127], v[120:123], v[80:95]
	v_add_u32_e32 v124, s34, v206
	s_waitcnt lgkmcnt(0)
	v_mfma_f32_32x32x16_bf16 v[64:79], v[128:131], v[120:123], v[64:79]
	ds_read_b128 v[120:123], v124 offset:49152
	ds_read_b128 v[124:127], v124 offset:61440
	s_waitcnt lgkmcnt(1)
	v_mfma_f32_32x32x16_bf16 v[80:95], v[120:123], v[116:119], v[80:95]
	v_add_u32_e32 v120, s34, v208
	s_waitcnt lgkmcnt(0)
	v_mfma_f32_32x32x16_bf16 v[64:79], v[124:127], v[116:119], v[64:79]
	ds_read_b128 v[116:119], v120 offset:49152
	ds_read_b128 v[120:123], v120 offset:61440
	s_waitcnt lgkmcnt(1)
	v_mfma_f32_32x32x16_bf16 v[80:95], v[116:119], v[112:115], v[80:95]
	v_add_u32_e32 v116, s34, v207
	s_waitcnt lgkmcnt(0)
	v_mfma_f32_32x32x16_bf16 v[64:79], v[120:123], v[112:115], v[64:79]
	ds_read_b128 v[112:115], v116 offset:49152
	ds_read_b128 v[116:119], v116 offset:61440
	v_exp_f32_e32 v120, v148
	v_exp_f32_e32 v121, v149
	s_waitcnt lgkmcnt(1)
	v_mfma_f32_32x32x16_bf16 v[80:95], v[112:115], v[108:111], v[80:95]
	v_add_u32_e32 v112, s34, v204
	s_waitcnt lgkmcnt(0)
	v_mfma_f32_32x32x16_bf16 v[64:79], v[116:119], v[108:111], v[64:79]
	ds_read_b128 v[108:111], v112 offset:49152
	ds_read_b128 v[112:115], v112 offset:61440
	v_exp_f32_e32 v116, v152
	v_exp_f32_e32 v117, v153
	v_exp_f32_e32 v118, v150
	v_exp_f32_e32 v119, v151
	s_waitcnt lgkmcnt(1)
	v_mfma_f32_32x32x16_bf16 v[80:95], v[108:111], v[104:107], v[80:95]
	v_add_u32_e32 v108, s34, v203
	s_waitcnt lgkmcnt(0)
	v_mfma_f32_32x32x16_bf16 v[64:79], v[112:115], v[104:107], v[64:79]
	ds_read_b128 v[104:107], v108 offset:49152
	ds_read_b128 v[108:111], v108 offset:61440
	v_exp_f32_e32 v112, v156
	v_exp_f32_e32 v113, v157
	v_exp_f32_e32 v114, v154
	v_exp_f32_e32 v115, v155
	s_waitcnt lgkmcnt(1)
	v_mfma_f32_32x32x16_bf16 v[80:95], v[104:107], v[100:103], v[80:95]
	v_add_u32_e32 v104, s34, v200
	s_waitcnt lgkmcnt(0)
	v_mfma_f32_32x32x16_bf16 v[64:79], v[108:111], v[100:103], v[64:79]
	ds_read_b128 v[100:103], v104 offset:49152
	ds_read_b128 v[104:107], v104 offset:61440
	v_exp_f32_e32 v108, v160
	v_exp_f32_e32 v109, v161
	v_exp_f32_e32 v110, v158
	v_exp_f32_e32 v111, v159
	s_waitcnt lgkmcnt(1)
	v_mfma_f32_32x32x16_bf16 v[80:95], v[100:103], v[96:99], v[80:95]
	v_add_u32_e32 v100, s34, v202
	s_waitcnt lgkmcnt(0)
	v_mfma_f32_32x32x16_bf16 v[64:79], v[104:107], v[96:99], v[64:79]
	v_add_u32_e32 v96, s34, v191
	ds_read_b128 v[96:99], v96 offset:49152
	ds_read_b128 v[100:103], v100 offset:61440
	ds_read_b128 v[104:107], v182
	s_waitcnt lgkmcnt(0)
	v_mfma_f32_32x32x16_bf16 v[80:95], v[96:99], v[104:107], v[80:95]
	v_add_u32_e32 v96, s34, v198
	ds_read_b128 v[96:99], v96 offset:49152
	v_mfma_f32_32x32x16_bf16 v[64:79], v[100:103], v[104:107], v[64:79]
	v_add_u32_e32 v100, s34, v201
	ds_read_b128 v[100:103], v100 offset:61440
	ds_read_b128 v[104:107], v181
	s_waitcnt lgkmcnt(0)
	v_mfma_f32_32x32x16_bf16 v[80:95], v[96:99], v[104:107], v[80:95]
	v_add_u32_e32 v96, s34, v187
	ds_read_b128 v[96:99], v96 offset:49152
	v_mfma_f32_32x32x16_bf16 v[64:79], v[100:103], v[104:107], v[64:79]
	v_add_u32_e32 v100, s34, v189
	ds_read_b128 v[100:103], v100 offset:61440
	ds_read_b128 v[104:107], v179
	s_waitcnt lgkmcnt(0)
	v_mfma_f32_32x32x16_bf16 v[80:95], v[96:99], v[104:107], v[80:95]
	v_add_u32_e32 v96, s34, v188
	ds_read_b128 v[96:99], v96 offset:49152
	v_mfma_f32_32x32x16_bf16 v[64:79], v[100:103], v[104:107], v[64:79]
	v_add_u32_e32 v100, s34, v190
	ds_read_b128 v[100:103], v100 offset:61440
	ds_read_b128 v[104:107], v177
	s_waitcnt lgkmcnt(0)
; __device__ __forceinline__ void partialSM(f32x16& p0, f32x16& p1, float& m_reg, float& mn, float& alpha) {
;   constexpr float C = SCALE * 1.4426950408889634f;
;   float pmax = p0[0];
; #pragma unroll
;   for (int r = 1; r < 16; ++r) pmax = fmaxf(pmax, p0[r]);
; #pragma unroll
;   for (int r = 0; r < 16; ++r) pmax = fmaxf(pmax, p1[r]);
;   { auto rr = __builtin_amdgcn_permlane32_swap(__float_as_uint(pmax), __float_as_uint(pmax), false, false);
;     pmax = fmaxf(__uint_as_float(rr[0]), __uint_as_float(rr[1])); }
;   if (__builtin_expect(__all(pmax - m_reg <= THR / SCALE), 1)) { mn = m_reg; alpha = 1.f; }
;   else { mn = fmaxf(m_reg, pmax); alpha = __builtin_amdgcn_exp2f((m_reg - mn) * C); m_reg = mn; }
; __device__ __forceinline__ void finishSM(f32x16& p0, f32x16& p1, float alpha, float& l_reg, bf16x8& pa0, bf16x8& pa1, bf16x8& pa2, bf16x8& pa3) {
; #pragma unroll
;   for (int r = 0; r < 16; ++r) p1[r] = __builtin_amdgcn_exp2f(p1[r]);
;   float ps = 0;
; #pragma unroll
;   for (int r = 0; r < 16; ++r) ps += p0[r];
; #pragma unroll
;   for (int r = 0; r < 16; ++r) ps += p1[r];
;   { auto rr = __builtin_amdgcn_permlane32_swap(__float_as_uint(ps), __float_as_uint(ps), false, false);
;     ps = __uint_as_float(rr[0]) + __uint_as_float(rr[1]); }
;   l_reg = l_reg * alpha + ps;
;     ...
;   PK4(p0, 0, pa0); PK4(p0, 8, pa1); PK4(p1, 0, pa2); PK4(p1, 8, pa3);
;     ...
; }
	v_mfma_f32_32x32x16_bf16 v[80:95], v[96:99], v[104:107], v[80:95]
	v_add_f32_e32 v96, 0, v225
	v_add_f32_e32 v96, v228, v96
	v_add_f32_e32 v96, v226, v96
	v_add_f32_e32 v96, v229, v96
	v_add_f32_e32 v96, v227, v96
	v_add_f32_e32 v96, v230, v96
	v_add_f32_e32 v96, v223, v96
	v_add_f32_e32 v96, v224, v96
	v_add_f32_e32 v96, v219, v96
	v_add_f32_e32 v96, v221, v96
	v_add_f32_e32 v96, v220, v96
	v_add_f32_e32 v96, v222, v96
	v_mfma_f32_32x32x16_bf16 v[64:79], v[100:103], v[104:107], v[64:79]
	v_exp_f32_e32 v106, v162
	v_add_f32_e32 v96, v215, v96
	v_exp_f32_e32 v107, v163
	v_add_f32_e32 v96, v217, v96
	v_add_f32_e32 v96, v216, v96
	v_add_f32_e32 v96, v218, v96
	v_add_f32_e32 v96, v106, v96
	v_add_f32_e32 v96, v107, v96
	v_add_f32_e32 v96, v108, v96
	v_add_f32_e32 v96, v109, v96
	v_add_f32_e32 v96, v110, v96
	v_add_f32_e32 v96, v111, v96
	v_add_f32_e32 v96, v112, v96
	v_add_f32_e32 v96, v113, v96
	v_add_f32_e32 v96, v114, v96
	v_add_f32_e32 v96, v115, v96
	v_add_f32_e32 v96, v116, v96
	v_add_f32_e32 v96, v117, v96
	v_add_f32_e32 v96, v118, v96
	v_add_f32_e32 v96, v119, v96
	v_add_f32_e32 v96, v120, v96
	v_add_f32_e32 v100, v121, v96
	v_mov_b32_e32 v101, v100
	v_cvt_pk_bf16_f32 v96, v225, v228
	v_cvt_pk_bf16_f32 v97, v226, v229
	v_cvt_pk_bf16_f32 v98, v227, v230
	v_cvt_pk_bf16_f32 v99, v223, v224
	s_nop 1
	v_permlane32_swap_b32_e32 v100, v101
	v_permlane32_swap_b32_e32 v96, v98
	v_permlane32_swap_b32_e32 v97, v99
	v_cvt_pk_bf16_f32 v102, v219, v221
	v_cvt_pk_bf16_f32 v103, v220, v222
	v_cvt_pk_bf16_f32 v104, v215, v217
	v_cvt_pk_bf16_f32 v105, v216, v218
	v_cvt_pk_bf16_f32 v106, v106, v107
	v_cvt_pk_bf16_f32 v107, v108, v109
	v_cvt_pk_bf16_f32 v108, v110, v111
	v_cvt_pk_bf16_f32 v109, v112, v113
	v_cvt_pk_bf16_f32 v110, v114, v115
	v_cvt_pk_bf16_f32 v111, v116, v117
	v_cvt_pk_bf16_f32 v112, v118, v119
	v_cvt_pk_bf16_f32 v113, v120, v121
	s_nop 0
	v_permlane32_swap_b32_e32 v102, v104
	v_permlane32_swap_b32_e32 v103, v105
	v_permlane32_swap_b32_e32 v106, v108
	v_permlane32_swap_b32_e32 v107, v109
	v_permlane32_swap_b32_e32 v110, v112
	v_permlane32_swap_b32_e32 v111, v113
	s_addk_i32 s31, 0xc000
	s_cmp_lg_u32 s30, 0
	s_cselect_b32 s18, s31, 0x8000
	v_add_u32_e32 v130, s18, v178
	ds_read_b64_tr_b16 v[114:115], v130 offset:0
	ds_read_b64_tr_b16 v[116:117], v130 offset:0x800
	ds_read_b64_tr_b16 v[118:119], v130 offset:0x1000
	ds_read_b64_tr_b16 v[120:121], v130 offset:0x1800
	ds_read_b64_tr_b16 v[122:123], v130 offset:0x2000
	ds_read_b64_tr_b16 v[124:125], v130 offset:0x2800
	ds_read_b64_tr_b16 v[126:127], v130 offset:0x3000
	ds_read_b64_tr_b16 v[128:129], v130 offset:0x3800
	s_waitcnt lgkmcnt(0)
	s_nop 0
	v_mfma_f32_32x32x16_bf16 v[32:47], v[96:99], v[114:117], v[32:47]
	ds_read_b64_tr_b16 v[114:115], v130 offset:0x200
	ds_read_b64_tr_b16 v[116:117], v130 offset:0xa00
	v_mfma_f32_32x32x16_bf16 v[32:47], v[102:105], v[118:121], v[32:47]
	ds_read_b64_tr_b16 v[118:119], v130 offset:0x1200
	ds_read_b64_tr_b16 v[120:121], v130 offset:0x1a00
	v_mfma_f32_32x32x16_bf16 v[32:47], v[106:109], v[122:125], v[32:47]
	ds_read_b64_tr_b16 v[122:123], v130 offset:0x2200
	ds_read_b64_tr_b16 v[124:125], v130 offset:0x2a00
	v_mfma_f32_32x32x16_bf16 v[32:47], v[110:113], v[126:129], v[32:47]
	ds_read_b64_tr_b16 v[126:127], v130 offset:0x3200
	ds_read_b64_tr_b16 v[128:129], v130 offset:0x3a00
	s_waitcnt lgkmcnt(0)
	v_mfma_f32_32x32x16_bf16 v[48:63], v[96:99], v[114:117], v[48:63]
	ds_read_b64_tr_b16 v[114:115], v130 offset:0x400
	ds_read_b64_tr_b16 v[116:117], v130 offset:0xc00
	v_mfma_f32_32x32x16_bf16 v[48:63], v[102:105], v[118:121], v[48:63]
	ds_read_b64_tr_b16 v[118:119], v130 offset:0x1400
	ds_read_b64_tr_b16 v[120:121], v130 offset:0x1c00
	v_mfma_f32_32x32x16_bf16 v[48:63], v[106:109], v[122:125], v[48:63]
	ds_read_b64_tr_b16 v[122:123], v130 offset:0x2400
	ds_read_b64_tr_b16 v[124:125], v130 offset:0x2c00
	v_mfma_f32_32x32x16_bf16 v[48:63], v[110:113], v[126:129], v[48:63]
	ds_read_b64_tr_b16 v[126:127], v130 offset:0x3400
	ds_read_b64_tr_b16 v[128:129], v130 offset:0x3c00
	s_waitcnt lgkmcnt(0)
	v_mfma_f32_32x32x16_bf16 v[16:31], v[96:99], v[114:117], v[16:31]
	ds_read_b64_tr_b16 v[114:115], v130 offset:0x600
	ds_read_b64_tr_b16 v[116:117], v130 offset:0xe00
	v_mfma_f32_32x32x16_bf16 v[16:31], v[102:105], v[118:121], v[16:31]
	ds_read_b64_tr_b16 v[118:119], v130 offset:0x1600
	ds_read_b64_tr_b16 v[120:121], v130 offset:0x1e00
	v_mfma_f32_32x32x16_bf16 v[16:31], v[106:109], v[122:125], v[16:31]
	ds_read_b64_tr_b16 v[122:123], v130 offset:0x2600
	ds_read_b64_tr_b16 v[124:125], v130 offset:0x2e00
	v_mfma_f32_32x32x16_bf16 v[16:31], v[110:113], v[126:129], v[16:31]
	ds_read_b64_tr_b16 v[126:127], v130 offset:0x3600
	ds_read_b64_tr_b16 v[128:129], v130 offset:0x3e00
	s_waitcnt lgkmcnt(0)
	v_mfma_f32_32x32x16_bf16 v[0:15], v[96:99], v[114:117], v[0:15]
	v_max_f32_e32 v96, v81, v81
	v_max_f32_e32 v97, v80, v80
	v_max_f32_e32 v96, v97, v96
	v_max3_f32 v96, v96, v82, v83
	v_max3_f32 v96, v96, v84, v85
	v_max3_f32 v96, v96, v86, v87
	v_max3_f32 v96, v96, v88, v89
	v_max3_f32 v96, v96, v90, v91
	v_max3_f32 v96, v96, v92, v93
	v_mfma_f32_32x32x16_bf16 v[0:15], v[102:105], v[118:121], v[0:15]
	v_max3_f32 v96, v96, v94, v95
	v_max3_f32 v96, v96, v64, v65
	v_max3_f32 v96, v96, v66, v67
	v_max3_f32 v96, v96, v68, v69
	v_max3_f32 v96, v96, v70, v71
	v_max3_f32 v96, v96, v72, v73
	v_max3_f32 v96, v96, v74, v75
	v_max3_f32 v96, v96, v76, v77
	v_mfma_f32_32x32x16_bf16 v[0:15], v[106:109], v[122:125], v[0:15]
	v_max3_f32 v96, v96, v78, v79
	v_mov_b32_e32 v97, v96
	s_nop 1
	v_permlane32_swap_b32_e32 v96, v97
	v_max_f32_e32 v97, v97, v97
	v_max_f32_e32 v96, v96, v96
	v_max_f32_e32 v96, v96, v97
	v_sub_f32_e32 v97, v96, v210
	v_cmp_ge_f32_e32 vcc, s15, v97
	v_max_f32_e32 v97, v210, v210
	v_max_f32_e32 v97, v97, v96
	v_mfma_f32_32x32x16_bf16 v[0:15], v[110:113], v[126:129], v[0:15]
	v_sub_f32_e32 v96, v210, v97
	v_mul_f32_e32 v96, 0x3dd53b94, v96
	v_exp_f32_e32 v96, v96
	s_cmp_eq_u64 vcc, exec
	s_cselect_b64 s[40:41], -1, 0
	v_cndmask_b32_e64 v96, v96, 1.0, s[40:41]
	v_cmp_gt_f32_e32 vcc, 1.0, v96
	s_cbranch_vccz .LBB0_1167
	s_and_saveexec_b64 s[18:19], s[38:39]
	ds_write_b32 v175, v96 offset:128
	s_or_b64 exec, exec, s[18:19]
	s_waitcnt lgkmcnt(0)
	v_add_u32_e32 v98, v173, v164
	ds_read_b128 v[102:105], v98 offset:224
	ds_read_b128 v[106:109], v98 offset:192
	ds_read_b128 v[110:113], v98 offset:160
	ds_read_b128 v[114:117], v98 offset:128
	s_waitcnt lgkmcnt(3)
	v_pk_mul_f32 v[44:45], v[44:45], v[102:103]
	s_waitcnt lgkmcnt(2)
	v_pk_mul_f32 v[40:41], v[40:41], v[106:107]
	s_waitcnt lgkmcnt(1)
	v_pk_mul_f32 v[36:37], v[36:37], v[110:111]
	v_pk_mul_f32 v[46:47], v[46:47], v[104:105]
	v_pk_mul_f32 v[42:43], v[42:43], v[108:109]
	v_pk_mul_f32 v[38:39], v[38:39], v[112:113]
	s_waitcnt lgkmcnt(0)
	v_pk_mul_f32 v[34:35], v[34:35], v[116:117]
	v_pk_mul_f32 v[32:33], v[32:33], v[114:115]
	v_pk_mul_f32 v[60:61], v[60:61], v[102:103]
	v_pk_mul_f32 v[56:57], v[56:57], v[106:107]
	v_pk_mul_f32 v[52:53], v[52:53], v[110:111]
	v_pk_mul_f32 v[62:63], v[62:63], v[104:105]
	v_pk_mul_f32 v[58:59], v[58:59], v[108:109]
	v_pk_mul_f32 v[54:55], v[54:55], v[112:113]
	v_pk_mul_f32 v[50:51], v[50:51], v[116:117]
	v_pk_mul_f32 v[48:49], v[48:49], v[114:115]
	v_pk_mul_f32 v[28:29], v[28:29], v[102:103]
	v_pk_mul_f32 v[24:25], v[24:25], v[106:107]
	v_pk_mul_f32 v[20:21], v[20:21], v[110:111]
	v_pk_mul_f32 v[30:31], v[30:31], v[104:105]
	v_pk_mul_f32 v[26:27], v[26:27], v[108:109]
	v_pk_mul_f32 v[22:23], v[22:23], v[112:113]
	v_pk_mul_f32 v[18:19], v[18:19], v[116:117]
	v_pk_mul_f32 v[16:17], v[16:17], v[114:115]
	v_pk_mul_f32 v[12:13], v[12:13], v[102:103]
	v_pk_mul_f32 v[8:9], v[8:9], v[106:107]
	v_pk_mul_f32 v[4:5], v[4:5], v[110:111]
	v_pk_mul_f32 v[14:15], v[14:15], v[104:105]
	v_pk_mul_f32 v[10:11], v[10:11], v[108:109]
	v_pk_mul_f32 v[6:7], v[6:7], v[112:113]
	v_pk_mul_f32 v[2:3], v[2:3], v[116:117]
	v_pk_mul_f32 v[0:1], v[0:1], v[114:115]
